# streaming (nt) cache hint on once-read row loads (final combine gather + x/x1 rows in norm, router, w_out epilogue) and on the final output stores
# speedup vs baseline: 1.0096x; 1.0067x over previous
.LBB0_223:
	v_lshl_add_u64 v[46:47], s[30:31], 0, v[78:79]
	v_lshl_add_u64 v[10:11], s[28:29], 0, v[74:75]
	v_add_co_u32_e64 v102, s[6:7], s36, v46
	v_lshl_add_u64 v[12:13], s[26:27], 0, v[74:75]
	ds_read_b128 v[2:5], v1
	ds_read_b128 v[6:9], v1 offset:8192
	v_lshl_add_u64 v[48:49], s[24:25], 0, v[78:79]
	global_load_dwordx4 v[42:45], v[10:11], off nt
	global_load_dwordx4 v[38:41], v[10:11], off offset:1024 nt
	global_load_dwordx4 v[34:37], v[10:11], off offset:2048 nt
	global_load_dwordx4 v[30:33], v[10:11], off offset:3072 nt
	global_load_dwordx4 v[26:29], v[12:13], off nt
	global_load_dwordx4 v[22:25], v[12:13], off offset:1024 nt
	global_load_dwordx4 v[18:21], v[12:13], off offset:2048 nt
	global_load_dwordx4 v[14:17], v[12:13], off offset:3072 nt
	v_add_co_u32_e32 v10, vcc, 0x1000, v10
	v_addc_co_u32_e64 v103, s[6:7], 0, v47, s[6:7]
	v_add_co_u32_e64 v76, s[6:7], s36, v48
	v_addc_co_u32_e32 v11, vcc, 0, v11, vcc
	s_nop 0
	v_addc_co_u32_e64 v77, s[6:7], 0, v49, s[6:7]
	global_load_dwordx4 v[70:73], v[10:11], off nt
	global_load_dwordx4 v[62:65], v[10:11], off offset:1024 nt
	global_load_dwordx4 v[46:49], v[10:11], off offset:3072 nt
	global_load_dwordx4 v[66:69], v[10:11], off offset:2048 nt
	v_add_co_u32_e32 v54, vcc, s33, v12
	v_mov_b32_e32 v117, 0
	s_nop 0
	v_addc_co_u32_e32 v55, vcc, 0, v13, vcc
	global_load_dwordx4 v[58:61], v[54:55], off nt
	global_load_dwordx4 v[50:53], v[54:55], off offset:1024 nt
	global_load_dwordx4 v[10:13], v[54:55], off offset:3072 nt
	s_nop 0
	global_load_dwordx4 v[54:57], v[54:55], off offset:2048 nt
	v_mov_b32_e32 v118, 0
	v_mov_b32_e32 v119, 0
	v_mov_b32_e32 v120, 0
	v_mov_b32_e32 v121, 0
	v_mov_b32_e32 v122, 0
	v_mov_b32_e32 v123, 0
	v_mov_b32_e32 v124, 0
	v_mov_b32_e32 v125, 0
	v_mov_b32_e32 v126, 0
	v_mov_b32_e32 v127, 0
	v_mov_b32_e32 v128, 0
	v_mov_b32_e32 v129, 0
	v_mov_b32_e32 v130, 0
	s_add_i32 s21, s21, 16
	v_mov_b32_e32 v131, 0
	v_mov_b32_e32 v132, 0
	s_add_u32 s24, s24, 0x8000
	s_addc_u32 s25, s25, 0
	s_add_u32 s26, s26, 0x20000
	s_addc_u32 s27, s27, 0
	s_add_u32 s28, s28, 0x20000
	s_addc_u32 s29, s29, 0
	s_add_u32 s30, s30, 0x8000
	s_addc_u32 s31, s31, 0
	s_cmp_lt_u32 s21, 48
	s_waitcnt vmcnt(15)
	v_mov_b32_e32 v136, v43
	s_waitcnt vmcnt(14)
	v_mov_b32_e32 v137, v39
	v_mov_b32_e32 v140, v45
	v_mov_b32_e32 v141, v41
	v_mov_b32_e32 v134, v42
	v_mov_b32_e32 v135, v38
	v_mov_b32_e32 v138, v44
	v_mov_b32_e32 v139, v40
	s_waitcnt vmcnt(13)
	v_pk_mul_f32 v[142:143], v[36:37], v[36:37]
	v_pk_mul_f32 v[144:145], v[34:35], v[34:35]
	s_waitcnt vmcnt(12)
	v_mul_f32_e32 v146, v31, v31
	v_mul_f32_e32 v148, v33, v33
	s_waitcnt vmcnt(11)
	v_mov_b32_e32 v152, v27
	s_waitcnt vmcnt(10)
	v_mov_b32_e32 v153, v23
	v_mov_b32_e32 v156, v29
	v_mov_b32_e32 v157, v25
	v_pk_mul_f32 v[136:137], v[136:137], v[136:137]
	v_pk_mul_f32 v[140:141], v[140:141], v[140:141]
	v_mov_b32_e32 v150, v26
	v_mov_b32_e32 v151, v22
	v_mov_b32_e32 v154, v28
	v_mov_b32_e32 v155, v24
	s_waitcnt vmcnt(9)
	v_pk_mul_f32 v[158:159], v[20:21], v[20:21]
	v_pk_mul_f32 v[160:161], v[18:19], v[18:19]
	s_waitcnt vmcnt(8)
	v_mul_f32_e32 v162, v15, v15
	v_pk_mov_b32 v[166:167], v[144:145], v[142:143] op_sel:[1,0]
	v_mov_b32_e32 v145, v143
	v_pk_fma_f32 v[142:143], v[30:31], v[30:31], v[146:147] op_sel_hi:[1,1,0]
	v_pk_fma_f32 v[146:147], v[32:33], v[32:33], v[148:149] op_sel_hi:[1,1,0]
	v_pk_mul_f32 v[148:149], v[152:153], v[152:153]
	v_pk_mul_f32 v[152:153], v[156:157], v[156:157]
	v_pk_fma_f32 v[134:135], v[134:135], v[134:135], v[136:137]
	v_pk_fma_f32 v[136:137], v[138:139], v[138:139], v[140:141]
	v_mul_f32_e32 v164, v17, v17
	v_pk_mov_b32 v[156:157], v[160:161], v[158:159] op_sel:[1,0]
	v_mov_b32_e32 v161, v159
	v_pk_fma_f32 v[158:159], v[14:15], v[14:15], v[162:163] op_sel_hi:[1,1,0]
	v_pk_add_f32 v[138:139], v[166:167], v[144:145]
	s_waitcnt vmcnt(6)
	v_pk_mul_f32 v[140:141], v[64:65], v[64:65]
	v_pk_mul_f32 v[144:145], v[62:63], v[62:63]
	v_pk_fma_f32 v[148:149], v[150:151], v[150:151], v[148:149]
	v_pk_fma_f32 v[150:151], v[154:155], v[154:155], v[152:153]
	v_pk_add_f32 v[134:135], v[134:135], v[136:137]
	v_pk_fma_f32 v[162:163], v[16:17], v[16:17], v[164:165] op_sel_hi:[1,1,0]
	v_mul_f32_e32 v133, v70, v70
	v_mul_f32_e32 v159, v71, v71
	s_waitcnt vmcnt(5)
	v_mul_f32_e32 v165, v46, v46
	v_mul_f32_e32 v167, v47, v47
	s_waitcnt vmcnt(4)
	v_mul_f32_e32 v164, v67, v67
	v_mul_f32_e32 v166, v69, v69
	v_pk_add_f32 v[152:153], v[156:157], v[160:161]
	v_pk_add_f32 v[136:137], v[138:139], v[138:139] op_sel:[0,1] op_sel_hi:[1,0]
	v_pk_mov_b32 v[138:139], v[144:145], v[140:141] op_sel:[1,0]
	v_mov_b32_e32 v145, v141
	v_pk_add_f32 v[148:149], v[148:149], v[150:151]
	v_pk_add_f32 v[134:135], v[134:135], v[134:135] op_sel:[0,1] op_sel_hi:[1,0]
	v_mul_f32_e32 v143, v72, v72
	v_mul_f32_e32 v147, v73, v73
	v_mul_f32_e32 v163, v48, v48
	v_mul_f32_e32 v168, v49, v49
	v_pk_fma_f32 v[140:141], v[66:67], v[66:67], v[164:165] op_sel_hi:[1,1,0]
	v_pk_fma_f32 v[154:155], v[68:69], v[68:69], v[166:167] op_sel_hi:[1,1,0]
	s_waitcnt vmcnt(3)
	v_mul_f32_e32 v161, v58, v58
	v_mul_f32_e32 v166, v59, v59
	v_mul_f32_e32 v169, v60, v60
	v_mul_f32_e32 v170, v61, v61
	v_pk_add_f32 v[150:151], v[152:153], v[152:153] op_sel:[0,1] op_sel_hi:[1,0]
	v_mov_b32_e32 v137, v159
	v_pk_add_f32 v[138:139], v[138:139], v[144:145]
	v_pk_add_f32 v[144:145], v[148:149], v[148:149] op_sel:[0,1] op_sel_hi:[1,0]
	v_mov_b32_e32 v135, v133
	s_waitcnt vmcnt(2)
	v_pk_mul_f32 v[152:153], v[52:53], v[52:53]
	v_pk_mul_f32 v[156:157], v[50:51], v[50:51]
	v_pk_add_f32 v[142:143], v[142:143], v[146:147]
	v_mov_b32_e32 v141, v163
	v_mov_b32_e32 v155, v168
	v_mov_b32_e32 v151, v166
	v_mov_b32_e32 v159, v169
	v_mov_b32_e32 v163, v170
	v_mov_b32_e32 v145, v161
	v_pk_add_f32 v[134:135], v[134:135], v[136:137]
	v_pk_mov_b32 v[146:147], v[156:157], v[152:153] op_sel:[1,0]
	v_mov_b32_e32 v157, v153
	v_pk_add_f32 v[140:141], v[140:141], v[154:155]
	v_pk_add_f32 v[154:155], v[158:159], v[162:163]
	v_pk_add_f32 v[136:137], v[144:145], v[150:151]
	v_pk_add_f32 v[134:135], v[134:135], v[142:143]
	s_waitcnt vmcnt(0)
	v_mul_f32_e32 v160, v55, v55
	v_mul_f32_e32 v164, v57, v57
	v_pk_add_f32 v[138:139], v[138:139], v[138:139] op_sel:[0,1] op_sel_hi:[1,0]
	v_pk_add_f32 v[146:147], v[146:147], v[156:157]
	v_pk_add_f32 v[136:137], v[136:137], v[154:155]
	v_pk_add_f32 v[134:135], v[134:135], v[134:135] op_sel:[0,1] op_sel_hi:[1,0]
	v_mul_f32_e32 v171, v10, v10
	v_mul_f32_e32 v172, v11, v11
	v_mul_f32_e32 v173, v12, v12
	v_mul_f32_e32 v174, v13, v13
	v_pk_fma_f32 v[148:149], v[54:55], v[54:55], v[160:161] op_sel_hi:[1,1,0]
	v_pk_fma_f32 v[152:153], v[56:57], v[56:57], v[164:165] op_sel_hi:[1,1,0]
	v_mov_b32_e32 v139, v167
	v_pk_add_f32 v[144:145], v[146:147], v[146:147] op_sel:[0,1] op_sel_hi:[1,0]
	v_pk_add_f32 v[136:137], v[136:137], v[136:137] op_sel:[0,1] op_sel_hi:[1,0]
	v_mov_b32_e32 v135, v165
	v_mov_b32_e32 v149, v173
	v_mov_b32_e32 v153, v174
	v_mov_b32_e32 v145, v172
	v_mov_b32_e32 v137, v171
	v_pk_add_f32 v[134:135], v[134:135], v[138:139]
	v_pk_add_f32 v[146:147], v[148:149], v[152:153]
	v_pk_add_f32 v[136:137], v[136:137], v[144:145]
	v_pk_add_f32 v[134:135], v[134:135], v[140:141]
	v_pk_add_f32 v[136:137], v[136:137], v[146:147]
	v_add_f32_e32 v133, v134, v135
	v_add_f32_e32 v134, v136, v137
	s_waitcnt lgkmcnt(1)
	s_nop 1
	v_add_f32_dpp v133, v133, v133 quad_perm:[1,0,3,2] row_mask:0xf bank_mask:0xf
	s_waitcnt lgkmcnt(0)
	s_nop 1
	v_add_f32_dpp v134, v134, v134 quad_perm:[1,0,3,2] row_mask:0xf bank_mask:0xf
	s_waitcnt lgkmcnt(1)
	s_nop 1
	v_add_f32_dpp v133, v133, v133 quad_perm:[2,3,0,1] row_mask:0xf bank_mask:0xf
	s_waitcnt lgkmcnt(0)
	s_nop 1
	v_add_f32_dpp v134, v134, v134 quad_perm:[2,3,0,1] row_mask:0xf bank_mask:0xf
	s_waitcnt lgkmcnt(1)
	s_nop 1
	v_add_f32_dpp v133, v133, v133 row_half_mirror row_mask:0xf bank_mask:0xf
	s_waitcnt lgkmcnt(0)
	s_nop 1
	v_add_f32_dpp v134, v134, v134 row_half_mirror row_mask:0xf bank_mask:0xf
	s_waitcnt lgkmcnt(1)
	s_nop 1
	v_add_f32_dpp v133, v133, v133 row_mirror row_mask:0xf bank_mask:0xf
	s_waitcnt lgkmcnt(0)
	s_nop 1
	v_add_f32_dpp v134, v134, v134 row_mirror row_mask:0xf bank_mask:0xf
	ds_bpermute_b32 v135, v115, v133
	ds_bpermute_b32 v136, v115, v134
	s_waitcnt lgkmcnt(1)
	v_add_f32_e32 v133, v133, v135
	s_waitcnt lgkmcnt(0)
	v_add_f32_e32 v134, v134, v136
	ds_bpermute_b32 v135, v116, v133
	ds_bpermute_b32 v136, v116, v134
	s_waitcnt lgkmcnt(1)
	v_add_f32_e32 v133, v133, v135
	s_waitcnt lgkmcnt(0)
	v_add_f32_e32 v134, v134, v136
	v_fmamk_f32 v133, v133, 0x3a000000, v108
	v_fmamk_f32 v134, v134, 0x3a000000, v108
	v_mul_f32_e32 v135, 0x4f800000, v133
	v_cmp_gt_f32_e64 s[6:7], s34, v133
	v_mul_f32_e32 v136, 0x4f800000, v134
	v_cmp_gt_f32_e32 vcc, s34, v134
	v_cndmask_b32_e64 v133, v133, v135, s[6:7]
	v_sqrt_f32_e32 v135, v133
	v_cndmask_b32_e32 v134, v134, v136, vcc
	v_sqrt_f32_e32 v136, v134
	v_add_u32_e32 v137, -1, v135
	v_add_u32_e32 v138, 1, v135
	v_add_u32_e32 v139, -1, v136
	v_fma_f32 v141, -v137, v135, v133
	v_add_u32_e32 v140, 1, v136
	v_fma_f32 v142, -v138, v135, v133
	v_fma_f32 v143, -v139, v136, v134
	v_cmp_ge_f32_e64 s[8:9], 0, v141
	v_fma_f32 v144, -v140, v136, v134
	v_cmp_lt_f32_e64 s[10:11], 0, v142
	v_cndmask_b32_e64 v135, v135, v137, s[8:9]
	v_cmp_ge_f32_e64 s[8:9], 0, v143
	v_cndmask_b32_e64 v135, v135, v138, s[10:11]
	v_mul_f32_e32 v137, 0x37800000, v135
	v_cndmask_b32_e64 v136, v136, v139, s[8:9]
	v_cmp_lt_f32_e64 s[8:9], 0, v144
	v_cndmask_b32_e64 v135, v135, v137, s[6:7]
	v_cmp_class_f32_e64 s[6:7], v133, v109
	v_cndmask_b32_e64 v136, v136, v140, s[8:9]
	v_mul_f32_e32 v138, 0x37800000, v136
	v_cndmask_b32_e32 v136, v136, v138, vcc
	v_cmp_class_f32_e32 vcc, v134, v109
	v_cndmask_b32_e64 v133, v135, v133, s[6:7]
	s_nop 0
	v_cndmask_b32_e32 v135, v136, v134, vcc
	v_div_scale_f32 v134, s[6:7], v133, v133, 1.0
	v_rcp_f32_e32 v139, v134
	v_div_scale_f32 v136, vcc, 1.0, v133, 1.0
	v_div_scale_f32 v137, s[6:7], v135, v135, 1.0
	v_fma_f32 v141, -v134, v139, 1.0
	v_fmac_f32_e32 v139, v141, v139
	v_mul_f32_e32 v141, v136, v139
	v_fma_f32 v143, -v134, v141, v136
	v_fmac_f32_e32 v141, v143, v139
	v_fma_f32 v134, -v134, v141, v136
	v_div_fmas_f32 v134, v134, v139, v141
	v_div_fixup_f32 v134, v134, v133, 1.0
	v_pk_mul_f32 v[42:43], v[42:43], v[134:135] op_sel_hi:[1,0]
	v_pk_mul_f32 v[44:45], v[44:45], v[134:135] op_sel_hi:[1,0]
	v_pk_fma_f32 v[2:3], v[2:3], v[42:43], v[6:7]
	v_pk_fma_f32 v[44:45], v[4:5], v[44:45], v[8:9]
	v_cvt_pk_bf16_f32 v4, v2, v3
	v_cvt_pk_fp8_f32 v117, v2, v3
	v_cvt_pk_bf16_f32 v4, v44, v45
	ds_read_b128 v[2:5], v1 offset:1024
	ds_read_b128 v[6:9], v1 offset:9216
	v_pk_mul_f32 v[38:39], v[38:39], v[134:135] op_sel_hi:[1,0]
	v_cvt_pk_fp8_f32 v117, v44, v45 op_sel:[0,0,1]
	v_pk_mul_f32 v[40:41], v[40:41], v[134:135] op_sel_hi:[1,0]
	v_pk_mul_f32 v[34:35], v[34:35], v[134:135] op_sel_hi:[1,0]
	s_waitcnt lgkmcnt(0)
	v_pk_fma_f32 v[2:3], v[2:3], v[38:39], v[6:7]
	v_pk_fma_f32 v[40:41], v[4:5], v[40:41], v[8:9]
	v_cvt_pk_fp8_f32 v118, v2, v3
	global_store_dword v[102:103], v117, off
	v_cvt_pk_bf16_f32 v2, v2, v3
	v_pk_mul_f32 v[36:37], v[36:37], v[134:135] op_sel_hi:[1,0]
	v_cvt_pk_bf16_f32 v2, v40, v41
	ds_read_b128 v[2:5], v1 offset:2048
	ds_read_b128 v[6:9], v1 offset:10240
	v_cvt_pk_fp8_f32 v118, v40, v41 op_sel:[0,0,1]
	v_pk_mul_f32 v[30:31], v[30:31], v[134:135] op_sel_hi:[1,0]
	v_pk_mul_f32 v[32:33], v[32:33], v[134:135] op_sel_hi:[1,0]
	v_pk_mul_f32 v[70:71], v[70:71], v[134:135] op_sel_hi:[1,0]
	s_waitcnt lgkmcnt(0)
	v_pk_fma_f32 v[36:37], v[36:37], v[4:5], v[8:9]
	v_pk_fma_f32 v[2:3], v[34:35], v[2:3], v[6:7]
	global_store_dword v[102:103], v118, off offset:256
	v_cvt_pk_bf16_f32 v4, v2, v3
	v_cvt_pk_fp8_f32 v119, v2, v3
	v_cvt_pk_bf16_f32 v4, v36, v37
	ds_read_b128 v[2:5], v1 offset:3072
	ds_read_b128 v[6:9], v1 offset:11264
	v_pk_mul_f32 v[72:73], v[72:73], v[134:135] op_sel_hi:[1,0]
	v_cvt_pk_fp8_f32 v119, v36, v37 op_sel:[0,0,1]
	v_pk_mul_f32 v[62:63], v[62:63], v[134:135] op_sel_hi:[1,0]
	v_pk_mul_f32 v[64:65], v[64:65], v[134:135] op_sel_hi:[1,0]
	s_waitcnt lgkmcnt(0)
	v_pk_fma_f32 v[2:3], v[30:31], v[2:3], v[6:7]
	v_pk_fma_f32 v[32:33], v[32:33], v[4:5], v[8:9]
	v_cvt_pk_fp8_f32 v120, v2, v3
	global_store_dword v[102:103], v119, off offset:512
	v_cvt_pk_bf16_f32 v2, v2, v3
	v_pk_mul_f32 v[66:67], v[66:67], v[134:135] op_sel_hi:[1,0]
	v_cvt_pk_bf16_f32 v2, v32, v33
	ds_read_b128 v[2:5], v1 offset:4096
	ds_read_b128 v[6:9], v1 offset:12288
	v_cvt_pk_fp8_f32 v120, v32, v33 op_sel:[0,0,1]
	v_pk_mul_f32 v[68:69], v[68:69], v[134:135] op_sel_hi:[1,0]
	v_rcp_f32_e32 v140, v137
	v_pk_mul_f32 v[46:47], v[46:47], v[134:135] op_sel_hi:[1,0]
	s_waitcnt lgkmcnt(0)
	v_pk_fma_f32 v[30:31], v[72:73], v[4:5], v[8:9]
	v_pk_fma_f32 v[2:3], v[70:71], v[2:3], v[6:7]
	global_store_dword v[102:103], v120, off offset:768
	v_cvt_pk_bf16_f32 v4, v2, v3
	v_cvt_pk_fp8_f32 v121, v2, v3
	v_cvt_pk_bf16_f32 v4, v30, v31
	ds_read_b128 v[2:5], v1 offset:5120
	ds_read_b128 v[6:9], v1 offset:13312
	v_fma_f32 v142, -v137, v140, 1.0
	v_cvt_pk_fp8_f32 v121, v30, v31 op_sel:[0,0,1]
	v_div_scale_f32 v138, s[6:7], 1.0, v135, 1.0
	s_waitcnt lgkmcnt(0)
	v_pk_fma_f32 v[2:3], v[62:63], v[2:3], v[6:7]
	v_pk_fma_f32 v[30:31], v[64:65], v[4:5], v[8:9]
	v_cvt_pk_fp8_f32 v122, v2, v3
	global_store_dword v[102:103], v121, off offset:1024
	v_cvt_pk_bf16_f32 v2, v2, v3
	v_fmac_f32_e32 v140, v142, v140
	v_cvt_pk_bf16_f32 v2, v30, v31
	ds_read_b128 v[2:5], v1 offset:6144
	ds_read_b128 v[6:9], v1 offset:14336
	v_cvt_pk_fp8_f32 v122, v30, v31 op_sel:[0,0,1]
	v_mul_f32_e32 v142, v138, v140
	v_pk_mul_f32 v[48:49], v[48:49], v[134:135] op_sel_hi:[1,0]
	v_fma_f32 v144, -v137, v142, v138
	s_waitcnt lgkmcnt(0)
	v_pk_fma_f32 v[30:31], v[68:69], v[4:5], v[8:9]
	v_pk_fma_f32 v[2:3], v[66:67], v[2:3], v[6:7]
	global_store_dword v[102:103], v122, off offset:1280
	v_cvt_pk_bf16_f32 v4, v2, v3
	v_cvt_pk_fp8_f32 v123, v2, v3
	v_cvt_pk_bf16_f32 v4, v30, v31
	ds_read_b128 v[2:5], v1 offset:7168
	ds_read_b128 v[6:9], v1 offset:15360
	v_fmac_f32_e32 v142, v144, v140
	v_cvt_pk_fp8_f32 v123, v30, v31 op_sel:[0,0,1]
	v_fma_f32 v136, -v137, v142, v138
	s_mov_b64 vcc, s[6:7]
	s_waitcnt lgkmcnt(0)
	v_pk_fma_f32 v[2:3], v[46:47], v[2:3], v[6:7]
	v_pk_fma_f32 v[30:31], v[48:49], v[4:5], v[8:9]
	v_cvt_pk_fp8_f32 v124, v2, v3
	global_store_dword v[102:103], v123, off offset:1536
	v_cvt_pk_bf16_f32 v2, v2, v3
	v_div_fmas_f32 v133, v136, v140, v142
	v_cvt_pk_bf16_f32 v2, v30, v31
	ds_read_b128 v[2:5], v1
	ds_read_b128 v[6:9], v1 offset:8192
	v_cvt_pk_fp8_f32 v124, v30, v31 op_sel:[0,0,1]
	v_div_fixup_f32 v134, v133, v135, 1.0
	v_pk_mul_f32 v[26:27], v[26:27], v[134:135] op_sel_hi:[1,0]
	v_pk_mul_f32 v[28:29], v[28:29], v[134:135] op_sel_hi:[1,0]
	s_waitcnt lgkmcnt(0)
	v_pk_fma_f32 v[2:3], v[2:3], v[26:27], v[6:7]
	v_pk_fma_f32 v[28:29], v[4:5], v[28:29], v[8:9]
	global_store_dword v[102:103], v124, off offset:1792
	v_cvt_pk_bf16_f32 v4, v2, v3
	v_cvt_pk_fp8_f32 v125, v2, v3
	v_cvt_pk_bf16_f32 v4, v28, v29
	ds_read_b128 v[2:5], v1 offset:1024
	ds_read_b128 v[6:9], v1 offset:9216
	v_pk_mul_f32 v[22:23], v[22:23], v[134:135] op_sel_hi:[1,0]
	v_cvt_pk_fp8_f32 v125, v28, v29 op_sel:[0,0,1]
	v_pk_mul_f32 v[24:25], v[24:25], v[134:135] op_sel_hi:[1,0]
	v_pk_mul_f32 v[18:19], v[18:19], v[134:135] op_sel_hi:[1,0]
	s_waitcnt lgkmcnt(0)
	v_pk_fma_f32 v[2:3], v[2:3], v[22:23], v[6:7]
	v_pk_fma_f32 v[24:25], v[4:5], v[24:25], v[8:9]
	v_cvt_pk_fp8_f32 v126, v2, v3
	global_store_dword v[76:77], v125, off
	v_cvt_pk_bf16_f32 v2, v2, v3
	v_pk_mul_f32 v[20:21], v[20:21], v[134:135] op_sel_hi:[1,0]
	v_cvt_pk_bf16_f32 v2, v24, v25
	ds_read_b128 v[2:5], v1 offset:2048
	ds_read_b128 v[6:9], v1 offset:10240
	v_cvt_pk_fp8_f32 v126, v24, v25 op_sel:[0,0,1]
	v_pk_mul_f32 v[14:15], v[14:15], v[134:135] op_sel_hi:[1,0]
	v_pk_mul_f32 v[16:17], v[16:17], v[134:135] op_sel_hi:[1,0]
	v_pk_mul_f32 v[42:43], v[58:59], v[134:135] op_sel_hi:[1,0]
	s_waitcnt lgkmcnt(0)
	v_pk_fma_f32 v[20:21], v[20:21], v[4:5], v[8:9]
	v_pk_fma_f32 v[2:3], v[18:19], v[2:3], v[6:7]
	global_store_dword v[76:77], v126, off offset:256
	v_cvt_pk_bf16_f32 v4, v2, v3
	v_cvt_pk_fp8_f32 v127, v2, v3
	v_cvt_pk_bf16_f32 v4, v20, v21
	ds_read_b128 v[2:5], v1 offset:3072
	ds_read_b128 v[6:9], v1 offset:11264
	v_pk_mul_f32 v[58:59], v[60:61], v[134:135] op_sel_hi:[1,0]
	v_cvt_pk_fp8_f32 v127, v20, v21 op_sel:[0,0,1]
	v_pk_mul_f32 v[50:51], v[50:51], v[134:135] op_sel_hi:[1,0]
	v_pk_mul_f32 v[52:53], v[52:53], v[134:135] op_sel_hi:[1,0]
	s_waitcnt lgkmcnt(0)
	v_pk_fma_f32 v[2:3], v[14:15], v[2:3], v[6:7]
	v_pk_fma_f32 v[16:17], v[16:17], v[4:5], v[8:9]
	v_cvt_pk_fp8_f32 v128, v2, v3
	global_store_dword v[76:77], v127, off offset:512
	v_cvt_pk_bf16_f32 v2, v2, v3
	v_pk_mul_f32 v[54:55], v[54:55], v[134:135] op_sel_hi:[1,0]
	v_cvt_pk_bf16_f32 v2, v16, v17
	ds_read_b128 v[2:5], v1 offset:4096
	ds_read_b128 v[6:9], v1 offset:12288
	v_cvt_pk_fp8_f32 v128, v16, v17 op_sel:[0,0,1]
	v_pk_mul_f32 v[56:57], v[56:57], v[134:135] op_sel_hi:[1,0]
	v_pk_mul_f32 v[10:11], v[10:11], v[134:135] op_sel_hi:[1,0]
	v_pk_mul_f32 v[12:13], v[12:13], v[134:135] op_sel_hi:[1,0]
	s_waitcnt lgkmcnt(0)
	v_pk_fma_f32 v[14:15], v[58:59], v[4:5], v[8:9]
	v_pk_fma_f32 v[2:3], v[42:43], v[2:3], v[6:7]
	global_store_dword v[76:77], v128, off offset:768
	v_cvt_pk_bf16_f32 v4, v2, v3
	v_cvt_pk_fp8_f32 v129, v2, v3
	v_cvt_pk_bf16_f32 v4, v14, v15
	ds_read_b128 v[2:5], v1 offset:5120
	ds_read_b128 v[6:9], v1 offset:13312
	v_cvt_pk_fp8_f32 v129, v14, v15 op_sel:[0,0,1]
	s_waitcnt lgkmcnt(0)
	v_pk_fma_f32 v[2:3], v[50:51], v[2:3], v[6:7]
	s_nop 0
	v_cvt_pk_fp8_f32 v130, v2, v3
	v_pk_fma_f32 v[14:15], v[52:53], v[4:5], v[8:9]
	global_store_dword v[76:77], v129, off offset:1024
	v_cvt_pk_bf16_f32 v2, v2, v3
	v_cvt_pk_fp8_f32 v130, v14, v15 op_sel:[0,0,1]
	v_cvt_pk_bf16_f32 v2, v14, v15
	ds_read_b128 v[2:5], v1 offset:6144
	ds_read_b128 v[6:9], v1 offset:14336
	global_store_dword v[76:77], v130, off offset:1280
	s_waitcnt lgkmcnt(0)
	v_pk_fma_f32 v[14:15], v[56:57], v[4:5], v[8:9]
	v_pk_fma_f32 v[16:17], v[54:55], v[2:3], v[6:7]
	s_nop 0
	v_cvt_pk_bf16_f32 v2, v16, v17
	v_cvt_pk_fp8_f32 v131, v16, v17
	v_cvt_pk_bf16_f32 v2, v14, v15
	ds_read_b128 v[2:5], v1 offset:7168
	ds_read_b128 v[6:9], v1 offset:15360
	v_cvt_pk_fp8_f32 v131, v14, v15 op_sel:[0,0,1]
	s_waitcnt lgkmcnt(0)
	v_pk_fma_f32 v[2:3], v[10:11], v[2:3], v[6:7]
	s_nop 0
	v_cvt_pk_fp8_f32 v132, v2, v3
	v_pk_fma_f32 v[4:5], v[12:13], v[4:5], v[8:9]
	global_store_dword v[76:77], v131, off offset:1536
	v_cvt_pk_bf16_f32 v2, v2, v3
	v_cvt_pk_fp8_f32 v132, v4, v5 op_sel:[0,0,1]
	v_cvt_pk_bf16_f32 v2, v4, v5
	global_store_dword v[76:77], v132, off offset:1792
	s_cbranch_scc1 .LBB0_223
	s_branch .LBB0_218

.LBB0_1083:
	v_mbcnt_lo_u32_b32 v20, -1, 0
	v_mbcnt_hi_u32_b32 v20, -1, v20
	s_lshl_b32 s35, s65, 8
	v_ashrrev_i32_e32 v2, 2, v20
	s_or_b32 s35, s35, s40
	v_and_b32_e32 v2, -4, v2
	s_lshl_b32 s2, s54, 8
	v_add_u32_e32 v2, s35, v2
	s_ashr_i32 s35, s54, 3
	s_add_i32 s2, s2, s39
	s_mul_hi_i32 s43, s35, 0xc000
	s_mul_i32 s35, s35, 0xc000
	v_readlane_b32 s56, v255, 5
	v_readlane_b32 s57, v255, 6
	s_add_u32 s42, s56, s35
	v_ashrrev_i32_e32 v3, 31, v2
	s_addc_u32 s43, s57, s43
	v_lshlrev_b64 v[18:19], 2, v[2:3]
	v_and_or_b32 v32, v20, 15, s2
	v_lshl_add_u64 v[2:3], s[42:43], 0, v[18:19]
	v_ashrrev_i32_e32 v33, 31, v32
	v_lshl_add_u64 v[4:5], v[2:3], 0, s[20:21]
	v_add_co_u32_e32 v2, vcc, s64, v2
	v_lshl_add_u64 v[20:21], s[8:9], 0, v[18:19]
	v_lshlrev_b64 v[22:23], 13, v[32:33]
	v_or_b32_e32 v186, 16, v32
	v_addc_co_u32_e32 v3, vcc, 0, v3, vcc
	v_lshl_add_u64 v[178:179], v[20:21], 0, v[22:23]
	v_ashrrev_i32_e32 v187, 31, v186
	global_load_dwordx4 v[10:13], v[4:5], off offset:64
	global_load_dwordx4 v[6:9], v[4:5], off offset:512
	global_load_dwordx4 v[14:17], v[2:3], off
	s_nop 0
	global_load_dwordx4 v[2:5], v[4:5], off offset:576
	s_nop 0
	global_load_dwordx4 v[24:27], v[178:179], off nt
	global_load_dwordx4 v[28:31], v[178:179], off offset:64 nt
	global_load_dwordx4 v[174:177], v[178:179], off offset:512 nt
	s_nop 0
	global_load_dwordx4 v[178:181], v[178:179], off offset:576 nt
	v_lshlrev_b64 v[228:229], 13, v[186:187]
	v_lshl_add_u64 v[198:199], v[20:21], 0, v[228:229]
	global_load_dwordx4 v[186:189], v[198:199], off nt
	global_load_dwordx4 v[190:193], v[198:199], off offset:64 nt
	global_load_dwordx4 v[194:197], v[198:199], off offset:512 nt
	s_nop 0
	global_load_dwordx4 v[198:201], v[198:199], off offset:576 nt
	v_or_b32_e32 v202, 32, v32
	v_ashrrev_i32_e32 v203, 31, v202
	v_lshlrev_b64 v[230:231], 13, v[202:203]
	v_lshl_add_u64 v[216:217], v[20:21], 0, v[230:231]
	global_load_dwordx4 v[202:205], v[216:217], off nt
	global_load_dwordx4 v[206:209], v[216:217], off offset:64 nt
	global_load_dwordx4 v[212:215], v[216:217], off offset:512 nt
	s_nop 0
	global_load_dwordx4 v[216:219], v[216:217], off offset:576 nt
	v_or_b32_e32 v32, 48, v32
	v_ashrrev_i32_e32 v33, 31, v32
	v_lshlrev_b64 v[232:233], 13, v[32:33]
	v_lshl_add_u64 v[32:33], v[20:21], 0, v[232:233]
	global_load_dwordx4 v[220:223], v[32:33], off nt
	global_load_dwordx4 v[224:227], v[32:33], off offset:64 nt
	v_pk_mul_f32 v[234:235], v[160:161], s[22:23] op_sel_hi:[1,0]
	v_pk_mul_f32 v[236:237], v[158:159], s[22:23] op_sel_hi:[1,0]
	global_load_dwordx4 v[158:161], v[32:33], off offset:512 nt
	v_pk_mul_f32 v[238:239], v[152:153], s[22:23] op_sel_hi:[1,0]
	v_pk_mul_f32 v[240:241], v[150:151], s[22:23] op_sel_hi:[1,0]
	global_load_dwordx4 v[150:153], v[32:33], off offset:576 nt
	v_pk_mul_f32 v[154:155], v[154:155], s[22:23] op_sel_hi:[1,0]
	v_pk_mul_f32 v[244:245], v[138:139], s[22:23] op_sel_hi:[1,0]
	v_lshl_add_u64 v[138:139], s[12:13], 0, v[22:23]
	v_pk_mul_f32 v[156:157], v[156:157], s[22:23] op_sel_hi:[1,0]
	v_pk_mul_f32 v[32:33], v[144:145], s[22:23] op_sel_hi:[1,0]
	v_pk_mul_f32 v[142:143], v[142:143], s[22:23] op_sel_hi:[1,0]
	v_pk_mul_f32 v[148:149], v[148:149], s[22:23] op_sel_hi:[1,0]
	v_pk_mul_f32 v[146:147], v[146:147], s[22:23] op_sel_hi:[1,0]
	v_lshl_add_u64 v[246:247], v[138:139], 0, v[18:19]
	v_lshl_add_u64 v[138:139], s[12:13], 0, v[228:229]
	v_pk_mul_f32 v[242:243], v[140:141], s[22:23] op_sel_hi:[1,0]
	v_lshl_add_u64 v[228:229], v[138:139], 0, v[18:19]
	v_pk_mul_f32 v[96:97], v[96:97], s[22:23] op_sel_hi:[1,0]
	v_pk_mul_f32 v[94:95], v[94:95], s[22:23] op_sel_hi:[1,0]
	v_pk_mul_f32 v[90:91], v[90:91], s[22:23] op_sel_hi:[1,0]
	s_andn2_b64 vcc, exec, s[4:5]
	s_mov_b64 s[4:5], -1
	s_waitcnt vmcnt(0)
	v_pk_fma_f32 v[28:29], v[154:155], v[10:11], v[28:29]
	v_pk_fma_f32 v[26:27], v[234:235], v[16:17], v[26:27]
	v_pk_fma_f32 v[24:25], v[236:237], v[14:15], v[24:25]
	v_pk_fma_f32 v[30:31], v[156:157], v[12:13], v[30:31]
	v_pk_fma_f32 v[140:141], v[238:239], v[8:9], v[176:177]
	v_pk_fma_f32 v[138:139], v[240:241], v[6:7], v[174:175]
	v_pk_fma_f32 v[144:145], v[32:33], v[4:5], v[180:181]
	v_pk_fma_f32 v[142:143], v[142:143], v[2:3], v[178:179]
	v_pk_fma_f32 v[148:149], v[148:149], v[16:17], v[188:189]
	v_pk_fma_f32 v[146:147], v[146:147], v[14:15], v[186:187]
	global_store_dwordx4 v[246:247], v[24:27], off
	global_store_dwordx4 v[246:247], v[28:31], off offset:64
	global_store_dwordx4 v[246:247], v[138:141], off offset:512
	global_store_dwordx4 v[246:247], v[142:145], off offset:576
	global_store_dwordx4 v[228:229], v[146:149], off
	v_pk_mul_f32 v[24:25], v[136:137], s[22:23] op_sel_hi:[1,0]
	v_pk_mul_f32 v[28:29], v[134:135], s[22:23] op_sel_hi:[1,0]
	v_pk_fma_f32 v[26:27], v[24:25], v[8:9], v[196:197]
	v_pk_fma_f32 v[24:25], v[28:29], v[6:7], v[194:195]
	global_store_dwordx4 v[228:229], v[24:27], off offset:512
	v_pk_mul_f32 v[28:29], v[126:127], s[22:23] op_sel_hi:[1,0]
	v_pk_fma_f32 v[32:33], v[242:243], v[12:13], v[192:193]
	v_pk_mul_f32 v[24:25], v[128:129], s[22:23] op_sel_hi:[1,0]
	v_pk_fma_f32 v[30:31], v[244:245], v[10:11], v[190:191]
	v_pk_fma_f32 v[26:27], v[24:25], v[4:5], v[200:201]
	v_pk_fma_f32 v[24:25], v[28:29], v[2:3], v[198:199]
	global_store_dwordx4 v[228:229], v[24:27], off offset:576
	v_pk_mul_f32 v[28:29], v[130:131], s[22:23] op_sel_hi:[1,0]
	global_store_dwordx4 v[228:229], v[30:33], off offset:64
	v_pk_mul_f32 v[24:25], v[132:133], s[22:23] op_sel_hi:[1,0]
	v_lshl_add_u64 v[154:155], v[22:23], 0, s[30:31]
	v_pk_fma_f32 v[26:27], v[24:25], v[16:17], v[204:205]
	v_pk_fma_f32 v[24:25], v[28:29], v[14:15], v[202:203]
	v_lshl_add_u64 v[28:29], s[12:13], 0, v[230:231]
	v_lshl_add_u64 v[28:29], v[28:29], 0, v[18:19]
	global_store_dwordx4 v[28:29], v[24:27], off
	v_pk_mul_f32 v[30:31], v[122:123], s[22:23] op_sel_hi:[1,0]
	v_lshl_add_u64 v[32:33], v[22:23], 0, s[24:25]
	v_pk_mul_f32 v[24:25], v[124:125], s[22:23] op_sel_hi:[1,0]
	v_lshl_add_u64 v[146:147], v[20:21], 0, v[154:155]
	v_pk_fma_f32 v[26:27], v[24:25], v[12:13], v[208:209]
	v_pk_fma_f32 v[24:25], v[30:31], v[10:11], v[206:207]
	global_store_dwordx4 v[28:29], v[24:27], off offset:64
	v_pk_mul_f32 v[30:31], v[118:119], s[22:23] op_sel_hi:[1,0]
	s_nop 0
	v_pk_mul_f32 v[24:25], v[120:121], s[22:23] op_sel_hi:[1,0]
	s_nop 0
	v_pk_fma_f32 v[26:27], v[24:25], v[8:9], v[214:215]
	v_pk_fma_f32 v[24:25], v[30:31], v[6:7], v[212:213]
	global_store_dwordx4 v[28:29], v[24:27], off offset:512
	v_pk_mul_f32 v[30:31], v[110:111], s[22:23] op_sel_hi:[1,0]
	s_nop 0
	v_pk_mul_f32 v[24:25], v[112:113], s[22:23] op_sel_hi:[1,0]
	s_nop 0
	v_pk_fma_f32 v[26:27], v[24:25], v[4:5], v[218:219]
	v_pk_fma_f32 v[24:25], v[30:31], v[2:3], v[216:217]
	global_store_dwordx4 v[28:29], v[24:27], off offset:576
	v_pk_mul_f32 v[28:29], v[114:115], s[22:23] op_sel_hi:[1,0]
	v_pk_mul_f32 v[30:31], v[106:107], s[22:23] op_sel_hi:[1,0]
	v_pk_mul_f32 v[24:25], v[116:117], s[22:23] op_sel_hi:[1,0]
	s_nop 0
	v_pk_fma_f32 v[26:27], v[24:25], v[16:17], v[222:223]
	v_pk_fma_f32 v[24:25], v[28:29], v[14:15], v[220:221]
	v_lshl_add_u64 v[28:29], s[12:13], 0, v[232:233]
	v_lshl_add_u64 v[28:29], v[28:29], 0, v[18:19]
	global_store_dwordx4 v[28:29], v[24:27], off
	s_nop 1
	v_pk_mul_f32 v[24:25], v[108:109], s[22:23] op_sel_hi:[1,0]
	s_nop 0
	v_pk_fma_f32 v[26:27], v[24:25], v[12:13], v[226:227]
	v_pk_fma_f32 v[24:25], v[30:31], v[10:11], v[224:225]
	global_store_dwordx4 v[28:29], v[24:27], off offset:64
	v_pk_mul_f32 v[30:31], v[102:103], s[22:23] op_sel_hi:[1,0]
	v_lshl_add_u64 v[102:103], v[20:21], 0, v[32:33]
	v_pk_mul_f32 v[24:25], v[104:105], s[22:23] op_sel_hi:[1,0]
	v_lshl_add_u64 v[32:33], s[12:13], 0, v[32:33]
	v_pk_fma_f32 v[26:27], v[24:25], v[8:9], v[160:161]
	v_pk_fma_f32 v[24:25], v[30:31], v[6:7], v[158:159]
	global_store_dwordx4 v[28:29], v[24:27], off offset:512
	v_pk_mul_f32 v[30:31], v[98:99], s[22:23] op_sel_hi:[1,0]
	v_lshl_add_u64 v[32:33], v[32:33], 0, v[18:19]
	v_pk_mul_f32 v[24:25], v[100:101], s[22:23] op_sel_hi:[1,0]
	s_nop 0
	v_pk_fma_f32 v[26:27], v[24:25], v[4:5], v[152:153]
	v_pk_fma_f32 v[24:25], v[30:31], v[2:3], v[150:151]
	global_store_dwordx4 v[28:29], v[24:27], off offset:576
	global_load_dwordx4 v[24:27], v[102:103], off nt
	s_nop 0
	global_load_dwordx4 v[28:31], v[102:103], off offset:64 nt
	global_load_dwordx4 v[98:101], v[102:103], off offset:512 nt
	s_nop 0
	global_load_dwordx4 v[102:105], v[102:103], off offset:576 nt
	v_lshl_add_u64 v[150:151], v[22:23], 0, s[26:27]
	v_lshl_add_u64 v[118:119], v[20:21], 0, v[150:151]
	global_load_dwordx4 v[106:109], v[118:119], off nt
	global_load_dwordx4 v[110:113], v[118:119], off offset:64 nt
	global_load_dwordx4 v[114:117], v[118:119], off offset:512 nt
	s_nop 0
	global_load_dwordx4 v[118:121], v[118:119], off offset:576 nt
	v_lshl_add_u64 v[152:153], v[22:23], 0, s[28:29]
	v_lshl_add_u64 v[134:135], v[20:21], 0, v[152:153]
	global_load_dwordx4 v[122:125], v[134:135], off nt
	global_load_dwordx4 v[126:129], v[134:135], off offset:64 nt
	global_load_dwordx4 v[130:133], v[134:135], off offset:512 nt
	s_nop 0
	global_load_dwordx4 v[134:137], v[134:135], off offset:576 nt
	s_nop 0
	global_load_dwordx4 v[20:23], v[146:147], off nt
	global_load_dwordx4 v[138:141], v[146:147], off offset:64 nt
	global_load_dwordx4 v[142:145], v[146:147], off offset:512 nt
	s_nop 0
	global_load_dwordx4 v[146:149], v[146:147], off offset:576 nt
	s_waitcnt vmcnt(15)
	v_pk_fma_f32 v[26:27], v[96:97], v[16:17], v[26:27]
	v_pk_fma_f32 v[24:25], v[94:95], v[14:15], v[24:25]
	global_store_dwordx4 v[32:33], v[24:27], off
	s_nop 1
	v_pk_mul_f32 v[24:25], v[92:93], s[22:23] op_sel_hi:[1,0]
	s_waitcnt vmcnt(15)
	v_pk_fma_f32 v[26:27], v[24:25], v[12:13], v[30:31]
	v_pk_fma_f32 v[24:25], v[90:91], v[10:11], v[28:29]
	global_store_dwordx4 v[32:33], v[24:27], off offset:64
	v_pk_mul_f32 v[28:29], v[86:87], s[22:23] op_sel_hi:[1,0]
	v_pk_mul_f32 v[30:31], v[74:75], s[22:23] op_sel_hi:[1,0]
	v_pk_mul_f32 v[24:25], v[88:89], s[22:23] op_sel_hi:[1,0]
	s_waitcnt vmcnt(15)
	v_pk_fma_f32 v[26:27], v[24:25], v[8:9], v[100:101]
	v_pk_fma_f32 v[24:25], v[28:29], v[6:7], v[98:99]
	global_store_dwordx4 v[32:33], v[24:27], off offset:512
	v_pk_mul_f32 v[28:29], v[78:79], s[22:23] op_sel_hi:[1,0]
	s_nop 0
	v_pk_mul_f32 v[24:25], v[80:81], s[22:23] op_sel_hi:[1,0]
	s_waitcnt vmcnt(15)
	v_pk_fma_f32 v[26:27], v[24:25], v[4:5], v[104:105]
	v_pk_fma_f32 v[24:25], v[28:29], v[2:3], v[102:103]
	global_store_dwordx4 v[32:33], v[24:27], off offset:576
	v_pk_mul_f32 v[28:29], v[82:83], s[22:23] op_sel_hi:[1,0]
	s_nop 0
	v_pk_mul_f32 v[24:25], v[84:85], s[22:23] op_sel_hi:[1,0]
	s_waitcnt vmcnt(15)
	v_pk_fma_f32 v[26:27], v[24:25], v[16:17], v[108:109]
	v_pk_fma_f32 v[24:25], v[28:29], v[14:15], v[106:107]
	v_lshl_add_u64 v[28:29], s[12:13], 0, v[150:151]
	v_lshl_add_u64 v[28:29], v[28:29], 0, v[18:19]
	global_store_dwordx4 v[28:29], v[24:27], off
	s_nop 1
	v_pk_mul_f32 v[24:25], v[76:77], s[22:23] op_sel_hi:[1,0]
	s_waitcnt vmcnt(15)
	v_pk_fma_f32 v[26:27], v[24:25], v[12:13], v[112:113]
	v_pk_fma_f32 v[24:25], v[30:31], v[10:11], v[110:111]
	global_store_dwordx4 v[28:29], v[24:27], off offset:64
	v_pk_mul_f32 v[30:31], v[70:71], s[22:23] op_sel_hi:[1,0]
	s_nop 0
	v_pk_mul_f32 v[24:25], v[72:73], s[22:23] op_sel_hi:[1,0]
	s_waitcnt vmcnt(15)
	v_pk_fma_f32 v[26:27], v[24:25], v[8:9], v[116:117]
	v_pk_fma_f32 v[24:25], v[30:31], v[6:7], v[114:115]
	global_store_dwordx4 v[28:29], v[24:27], off offset:512
	v_pk_mul_f32 v[30:31], v[62:63], s[22:23] op_sel_hi:[1,0]
	s_nop 0
	v_pk_mul_f32 v[24:25], v[64:65], s[22:23] op_sel_hi:[1,0]
	s_waitcnt vmcnt(15)
	v_pk_fma_f32 v[26:27], v[24:25], v[4:5], v[120:121]
	v_pk_fma_f32 v[24:25], v[30:31], v[2:3], v[118:119]
	global_store_dwordx4 v[28:29], v[24:27], off offset:576
	v_pk_mul_f32 v[28:29], v[66:67], s[22:23] op_sel_hi:[1,0]
	v_pk_mul_f32 v[30:31], v[58:59], s[22:23] op_sel_hi:[1,0]
	v_pk_mul_f32 v[24:25], v[68:69], s[22:23] op_sel_hi:[1,0]
	s_waitcnt vmcnt(15)
	v_pk_fma_f32 v[26:27], v[24:25], v[16:17], v[124:125]
	v_pk_fma_f32 v[24:25], v[28:29], v[14:15], v[122:123]
	v_lshl_add_u64 v[28:29], s[12:13], 0, v[152:153]
	v_lshl_add_u64 v[28:29], v[28:29], 0, v[18:19]
	global_store_dwordx4 v[28:29], v[24:27], off
	s_nop 1
	v_pk_mul_f32 v[24:25], v[60:61], s[22:23] op_sel_hi:[1,0]
	s_waitcnt vmcnt(15)
	v_pk_fma_f32 v[26:27], v[24:25], v[12:13], v[128:129]
	v_pk_fma_f32 v[24:25], v[30:31], v[10:11], v[126:127]
	global_store_dwordx4 v[28:29], v[24:27], off offset:64
	v_pk_mul_f32 v[30:31], v[54:55], s[22:23] op_sel_hi:[1,0]
	s_nop 0
	v_pk_mul_f32 v[24:25], v[56:57], s[22:23] op_sel_hi:[1,0]
	s_waitcnt vmcnt(15)
	v_pk_fma_f32 v[26:27], v[24:25], v[8:9], v[132:133]
	v_pk_fma_f32 v[24:25], v[30:31], v[6:7], v[130:131]
	global_store_dwordx4 v[28:29], v[24:27], off offset:512
	v_pk_mul_f32 v[30:31], v[46:47], s[22:23] op_sel_hi:[1,0]
	s_nop 0
	v_pk_mul_f32 v[24:25], v[48:49], s[22:23] op_sel_hi:[1,0]
	s_waitcnt vmcnt(15)
	v_pk_fma_f32 v[26:27], v[24:25], v[4:5], v[136:137]
	v_pk_fma_f32 v[24:25], v[30:31], v[2:3], v[134:135]
	global_store_dwordx4 v[28:29], v[24:27], off offset:576
	s_nop 1
	v_pk_mul_f32 v[26:27], v[50:51], s[22:23] op_sel_hi:[1,0]
	v_pk_mul_f32 v[24:25], v[52:53], s[22:23] op_sel_hi:[1,0]
	s_waitcnt vmcnt(15)
	v_pk_fma_f32 v[14:15], v[26:27], v[14:15], v[20:21]
	v_lshl_add_u64 v[20:21], s[12:13], 0, v[154:155]
	v_pk_fma_f32 v[16:17], v[24:25], v[16:17], v[22:23]
	v_lshl_add_u64 v[18:19], v[20:21], 0, v[18:19]
	global_store_dwordx4 v[18:19], v[14:17], off
	s_nop 1
	v_pk_mul_f32 v[14:15], v[44:45], s[22:23] op_sel_hi:[1,0]
	v_pk_mul_f32 v[16:17], v[42:43], s[22:23] op_sel_hi:[1,0]
	s_waitcnt vmcnt(15)
	v_pk_fma_f32 v[12:13], v[14:15], v[12:13], v[140:141]
	v_pk_fma_f32 v[10:11], v[16:17], v[10:11], v[138:139]
	global_store_dwordx4 v[18:19], v[10:13], off offset:64
	s_nop 1
	v_pk_mul_f32 v[10:11], v[40:41], s[22:23] op_sel_hi:[1,0]
	v_pk_mul_f32 v[12:13], v[38:39], s[22:23] op_sel_hi:[1,0]
	s_waitcnt vmcnt(15)
	v_pk_fma_f32 v[8:9], v[10:11], v[8:9], v[144:145]
	v_pk_fma_f32 v[6:7], v[12:13], v[6:7], v[142:143]
	global_store_dwordx4 v[18:19], v[6:9], off offset:512
	s_nop 1
	v_pk_mul_f32 v[6:7], v[36:37], s[22:23] op_sel_hi:[1,0]
	v_pk_mul_f32 v[8:9], v[34:35], s[22:23] op_sel_hi:[1,0]
	s_waitcnt vmcnt(15)
	v_pk_fma_f32 v[4:5], v[6:7], v[4:5], v[148:149]
	v_pk_fma_f32 v[2:3], v[8:9], v[2:3], v[146:147]
	global_store_dwordx4 v[18:19], v[2:5], off offset:576
	s_cbranch_vccnz .LBB0_1072
	s_andn2_b64 vcc, exec, s[10:11]
	s_cbranch_vccnz .LBB0_1071
	s_barrier
	s_branch .LBB0_1071

.LBB0_1157:
	s_lshl_b32 s35, s37, 4
	s_add_i32 s10, s36, s35
	s_ashr_i32 s11, s10, 31
	s_lshl_b64 s[38:39], s[10:11], 13
	v_lshl_add_u64 v[34:35], v[114:115], 0, s[38:39]
	global_load_dwordx4 v[96:99], v[34:35], off nt
	global_load_dwordx4 v[92:95], v[34:35], off offset:1024 nt
	global_load_dwordx4 v[88:91], v[34:35], off offset:2048 nt
	global_load_dwordx4 v[84:87], v[34:35], off offset:3072 nt
	s_or_b32 s10, s10, 1
	s_ashr_i32 s11, s10, 31
	s_lshl_b64 s[10:11], s[10:11], 13
	v_add_co_u32_e32 v34, vcc, 0x1000, v34
	v_lshl_add_u64 v[36:37], v[114:115], 0, s[10:11]
	s_nop 0
	v_addc_co_u32_e32 v35, vcc, 0, v35, vcc
	global_load_dwordx4 v[64:67], v[36:37], off nt
	global_load_dwordx4 v[60:63], v[36:37], off offset:1024 nt
	global_load_dwordx4 v[80:83], v[34:35], off nt
	global_load_dwordx4 v[76:79], v[34:35], off offset:1024 nt
	global_load_dwordx4 v[68:71], v[34:35], off offset:3072 nt
	global_load_dwordx4 v[72:75], v[34:35], off offset:2048 nt
	global_load_dwordx4 v[56:59], v[36:37], off offset:2048 nt
	global_load_dwordx4 v[52:55], v[36:37], off offset:3072 nt
	v_add_co_u32_e32 v34, vcc, s30, v36
	s_add_i32 s35, s35, s34
	s_nop 0
	v_addc_co_u32_e32 v35, vcc, 0, v37, vcc
	global_load_dwordx4 v[48:51], v[34:35], off nt
	global_load_dwordx4 v[42:45], v[34:35], off offset:1024 nt
	global_load_dwordx4 v[38:41], v[34:35], off offset:2048 nt
	s_nop 0
	global_load_dwordx4 v[34:37], v[34:35], off offset:3072 nt
	s_mov_b32 s2, 0
	s_waitcnt vmcnt(15)
	v_mov_b32_e32 v190, v97
	s_waitcnt vmcnt(14)
	v_mov_b32_e32 v191, v93
	v_mov_b32_e32 v194, v99
	v_mov_b32_e32 v195, v95
	v_mov_b32_e32 v46, v96
	v_mov_b32_e32 v47, v92
	v_mov_b32_e32 v192, v98
	v_mov_b32_e32 v193, v94
	s_waitcnt vmcnt(13)
	v_pk_mul_f32 v[196:197], v[90:91], v[90:91]
	v_pk_mul_f32 v[198:199], v[88:89], v[88:89]
	v_pk_mul_f32 v[190:191], v[190:191], v[190:191]
	v_pk_mul_f32 v[194:195], v[194:195], v[194:195]
	v_pk_mov_b32 v[202:203], v[198:199], v[196:197] op_sel:[1,0]
	v_mov_b32_e32 v199, v197
	v_pk_fma_f32 v[46:47], v[46:47], v[46:47], v[190:191]
	v_pk_fma_f32 v[190:191], v[192:193], v[192:193], v[194:195]
	s_waitcnt vmcnt(12)
	v_mul_f32_e32 v100, v85, v85
	v_mul_f32_e32 v200, v87, v87
	v_pk_add_f32 v[192:193], v[202:203], v[198:199]
	v_pk_add_f32 v[46:47], v[46:47], v[190:191]
	v_pk_fma_f32 v[196:197], v[84:85], v[84:85], v[100:101] op_sel_hi:[1,1,0]
	v_pk_fma_f32 v[200:201], v[86:87], v[86:87], v[200:201] op_sel_hi:[1,1,0]
	s_waitcnt vmcnt(9)
	v_mul_f32_e32 v189, v80, v80
	v_mul_f32_e32 v208, v81, v81
	v_pk_add_f32 v[190:191], v[192:193], v[192:193] op_sel:[0,1] op_sel_hi:[1,0]
	v_pk_add_f32 v[46:47], v[46:47], v[46:47] op_sel:[0,1] op_sel_hi:[1,0]
	v_mul_f32_e32 v197, v82, v82
	v_mul_f32_e32 v201, v83, v83
	s_waitcnt vmcnt(8)
	v_pk_mul_f32 v[194:195], v[78:79], v[78:79]
	v_pk_mul_f32 v[198:199], v[76:77], v[76:77]
	v_mov_b32_e32 v191, v208
	v_mov_b32_e32 v47, v189
	v_pk_mov_b32 v[192:193], v[198:199], v[194:195] op_sel:[1,0]
	v_mov_b32_e32 v199, v195
	v_pk_add_f32 v[196:197], v[196:197], v[200:201]
	v_pk_add_f32 v[46:47], v[46:47], v[190:191]
	s_waitcnt vmcnt(6)
	v_mul_f32_e32 v100, v73, v73
	v_mul_f32_e32 v202, v75, v75
	v_pk_add_f32 v[192:193], v[192:193], v[198:199]
	v_pk_add_f32 v[46:47], v[46:47], v[196:197]
	v_mul_f32_e32 v209, v68, v68
	v_mul_f32_e32 v212, v69, v69
	v_mul_f32_e32 v213, v70, v70
	v_mul_f32_e32 v214, v71, v71
	v_pk_fma_f32 v[194:195], v[72:73], v[72:73], v[100:101] op_sel_hi:[1,1,0]
	v_pk_fma_f32 v[202:203], v[74:75], v[74:75], v[202:203] op_sel_hi:[1,1,0]
	v_pk_add_f32 v[192:193], v[192:193], v[192:193] op_sel:[0,1] op_sel_hi:[1,0]
	v_pk_add_f32 v[46:47], v[46:47], v[46:47] op_sel:[0,1] op_sel_hi:[1,0]
	v_mov_b32_e32 v195, v213
	v_mov_b32_e32 v203, v214
	v_mov_b32_e32 v193, v212
	v_mov_b32_e32 v47, v209
	v_mov_b32_e32 v206, v65
	v_mov_b32_e32 v207, v61
	v_pk_add_f32 v[194:195], v[194:195], v[202:203]
	v_pk_add_f32 v[46:47], v[46:47], v[192:193]
	v_mov_b32_e32 v192, v67
	v_mov_b32_e32 v193, v63
	v_mov_b32_e32 v204, v64
	v_mov_b32_e32 v205, v60
	v_pk_mul_f32 v[206:207], v[206:207], v[206:207]
	v_pk_add_f32 v[46:47], v[46:47], v[194:195]
	v_mov_b32_e32 v190, v66
	v_mov_b32_e32 v191, v62
	v_pk_mul_f32 v[192:193], v[192:193], v[192:193]
	v_add_f32_e32 v189, v46, v47
	v_pk_fma_f32 v[46:47], v[204:205], v[204:205], v[206:207]
	v_pk_fma_f32 v[190:191], v[190:191], v[190:191], v[192:193]
	s_waitcnt vmcnt(5)
	v_pk_mul_f32 v[192:193], v[56:57], v[56:57]
	v_pk_add_f32 v[46:47], v[46:47], v[190:191]
	v_pk_mul_f32 v[190:191], v[58:59], v[58:59]
	s_waitcnt vmcnt(3)
	v_mul_f32_e32 v100, v48, v48
	v_pk_mov_b32 v[194:195], v[192:193], v[190:191] op_sel:[1,0]
	v_mov_b32_e32 v193, v191
	v_pk_add_f32 v[190:191], v[194:195], v[192:193]
	v_mul_f32_e32 v192, v49, v49
	v_pk_add_f32 v[46:47], v[46:47], v[46:47] op_sel:[0,1] op_sel_hi:[1,0]
	v_pk_add_f32 v[190:191], v[190:191], v[190:191] op_sel:[0,1] op_sel_hi:[1,0]
	v_mov_b32_e32 v47, v100
	v_mov_b32_e32 v191, v192
	v_mul_f32_e32 v100, v53, v53
	v_mul_f32_e32 v193, v50, v50
	v_pk_add_f32 v[46:47], v[46:47], v[190:191]
	v_pk_fma_f32 v[190:191], v[52:53], v[52:53], v[100:101] op_sel_hi:[1,1,0]
	v_mul_f32_e32 v100, v55, v55
	v_mov_b32_e32 v191, v193
	v_pk_fma_f32 v[192:193], v[54:55], v[54:55], v[100:101] op_sel_hi:[1,1,0]
	s_waitcnt lgkmcnt(0)
	s_nop 1
	v_add_f32_dpp v100, v189, v189 quad_perm:[1,0,3,2] row_mask:0xf bank_mask:0xf
	v_mul_f32_e32 v194, v51, v51
	v_mov_b32_e32 v193, v194
	v_pk_add_f32 v[190:191], v[190:191], v[192:193]
	s_waitcnt vmcnt(2)
	v_pk_mul_f32 v[192:193], v[42:43], v[42:43]
	s_waitcnt lgkmcnt(0)
	s_nop 1
	v_add_f32_dpp v100, v100, v100 quad_perm:[2,3,0,1] row_mask:0xf bank_mask:0xf
	v_pk_add_f32 v[46:47], v[46:47], v[190:191]
	v_pk_mul_f32 v[190:191], v[44:45], v[44:45]
	v_pk_add_f32 v[46:47], v[46:47], v[46:47] op_sel:[0,1] op_sel_hi:[1,0]
	v_pk_mov_b32 v[194:195], v[192:193], v[190:191] op_sel:[1,0]
	s_waitcnt lgkmcnt(0)
	s_nop 1
	v_add_f32_dpp v100, v100, v100 row_half_mirror row_mask:0xf bank_mask:0xf
	v_mov_b32_e32 v193, v191
	v_pk_add_f32 v[190:191], v[194:195], v[192:193]
	s_waitcnt vmcnt(0)
	v_mul_f32_e32 v192, v34, v34
	v_mov_b32_e32 v47, v192
	s_waitcnt lgkmcnt(0)
	s_nop 1
	v_add_f32_dpp v189, v100, v100 row_mirror row_mask:0xf bank_mask:0xf
	ds_bpermute_b32 v192, v155, v189
	v_mul_f32_e32 v193, v35, v35
	v_pk_add_f32 v[190:191], v[190:191], v[190:191] op_sel:[0,1] op_sel_hi:[1,0]
	v_mul_f32_e32 v100, v39, v39
	v_mov_b32_e32 v191, v193
	s_waitcnt lgkmcnt(0)
	v_add_f32_e32 v189, v189, v192
	ds_bpermute_b32 v196, v156, v189
	v_pk_add_f32 v[46:47], v[46:47], v[190:191]
	v_pk_fma_f32 v[190:191], v[38:39], v[38:39], v[100:101] op_sel_hi:[1,1,0]
	v_mul_f32_e32 v100, v41, v41
	v_pk_fma_f32 v[192:193], v[40:41], v[40:41], v[100:101] op_sel_hi:[1,1,0]
	s_waitcnt lgkmcnt(0)
	v_add_f32_e32 v100, v189, v196
	v_fmamk_f32 v100, v100, 0x3a000000, v182
	v_mul_f32_e32 v189, 0x4f800000, v100
	v_cmp_gt_f32_e32 vcc, s31, v100
	v_mul_f32_e32 v194, v36, v36
	v_mul_f32_e32 v195, v37, v37
	v_cndmask_b32_e32 v100, v100, v189, vcc
	v_sqrt_f32_e32 v189, v100
	v_mov_b32_e32 v191, v194
	v_mov_b32_e32 v193, v195
	v_pk_add_f32 v[190:191], v[190:191], v[192:193]
	s_nop 0
	v_pk_add_f32 v[46:47], v[46:47], v[190:191]
	v_add_u32_e32 v190, -1, v189
	v_fma_f32 v191, -v190, v189, v100
	v_cmp_ge_f32_e64 s[10:11], 0, v191
	v_add_u32_e32 v191, 1, v189
	v_add_f32_e32 v194, v46, v47
	v_cndmask_b32_e64 v190, v189, v190, s[10:11]
	v_fma_f32 v189, -v191, v189, v100
	v_cmp_lt_f32_e64 s[10:11], 0, v189
	s_nop 1
	v_cndmask_b32_e64 v189, v190, v191, s[10:11]
	v_mul_f32_e32 v190, 0x37800000, v189
	v_cndmask_b32_e32 v189, v189, v190, vcc
	v_cmp_class_f32_e32 vcc, v100, v183
	s_nop 1
	v_cndmask_b32_e32 v100, v189, v100, vcc
	v_div_scale_f32 v189, s[10:11], v100, v100, 1.0
	v_rcp_f32_e32 v190, v189
	s_add_i32 s10, s35, s14
	s_ashr_i32 s11, s10, 31
	s_lshl_b64 s[10:11], s[10:11], 11
	v_fma_f32 v46, -v189, v190, 1.0
	v_fmac_f32_e32 v190, v46, v190
	v_div_scale_f32 v46, vcc, 1.0, v100, 1.0
	v_mul_f32_e32 v47, v46, v190
	v_fma_f32 v191, -v189, v47, v46
	v_fmac_f32_e32 v47, v191, v190
	v_fma_f32 v46, -v189, v47, v46
	v_div_fmas_f32 v46, v46, v190, v47
	v_div_fixup_f32 v100, v46, v100, 1.0
	v_pk_mul_f32 v[46:47], v[96:97], v[100:101] op_sel_hi:[1,0]
	v_mov_b32_e32 v189, v101
	v_pk_fma_f32 v[190:191], v[120:121], v[46:47], v[2:3]
	v_pk_mul_f32 v[46:47], v[98:99], v[100:101] op_sel_hi:[1,0]
	v_cvt_pk_fp8_f32 v189, v190, v191
	v_pk_fma_f32 v[98:99], v[118:119], v[46:47], v[4:5]
	v_lshl_add_u64 v[96:97], v[116:117], 0, s[10:11]
	v_pk_mul_f32 v[92:93], v[92:93], v[100:101] op_sel_hi:[1,0]
	v_cvt_pk_fp8_f32 v189, v98, v99 op_sel:[0,0,1]
	v_pk_fma_f32 v[92:93], v[124:125], v[92:93], v[6:7]
	v_pk_mul_f32 v[94:95], v[94:95], v[100:101] op_sel_hi:[1,0]
	v_pk_mul_f32 v[88:89], v[88:89], v[100:101] op_sel_hi:[1,0]
	global_store_dword v[96:97], v189, off
	v_cvt_pk_bf16_f32 v192, v190, v191
	v_cvt_pk_bf16_f32 v193, v98, v99
	v_pk_fma_f32 v[94:95], v[122:123], v[94:95], v[8:9]
	v_lshlrev_b32_e32 v47, 16, v192
	v_sub_f32_e32 v47, v190, v47
	v_and_b32_e32 v189, 0xffff0000, v192
	v_sub_f32_e32 v189, v191, v189
	v_cvt_pk_bf16_f32 v190, v47, v189
	v_lshlrev_b32_e32 v47, 16, v193
	v_sub_f32_e32 v47, v98, v47
	v_and_b32_e32 v98, 0xffff0000, v193
	v_sub_f32_e32 v98, v99, v98
	v_cvt_pk_bf16_f32 v191, v47, v98
	v_mov_b32_e32 v47, v101
	v_cvt_pk_fp8_f32 v47, v92, v93
	v_add_u32_e32 v98, s15, v163
	ds_write_b64 v98, v[192:193]
	v_add_u32_e32 v98, s26, v163
	v_cvt_pk_fp8_f32 v47, v94, v95 op_sel:[0,0,1]
	ds_write_b64 v98, v[190:191]
	v_pk_fma_f32 v[88:89], v[128:129], v[88:89], v[10:11]
	v_pk_mul_f32 v[90:91], v[90:91], v[100:101] op_sel_hi:[1,0]
	global_store_dword v[96:97], v47, off offset:256
	v_cvt_pk_bf16_f32 v98, v92, v93
	v_cvt_pk_bf16_f32 v99, v94, v95
	v_pk_fma_f32 v[90:91], v[126:127], v[90:91], v[12:13]
	v_lshlrev_b32_e32 v47, 16, v98
	v_sub_f32_e32 v47, v92, v47
	v_and_b32_e32 v92, 0xffff0000, v98
	v_sub_f32_e32 v92, v93, v92
	v_cvt_pk_bf16_f32 v92, v47, v92
	v_lshlrev_b32_e32 v47, 16, v99
	v_and_b32_e32 v93, 0xffff0000, v99
	v_sub_f32_e32 v47, v94, v47
	v_sub_f32_e32 v93, v95, v93
	v_cvt_pk_bf16_f32 v93, v47, v93
	v_mov_b32_e32 v47, v101
	v_cvt_pk_fp8_f32 v47, v88, v89
	v_add_u32_e32 v94, s15, v164
	ds_write_b64 v94, v[98:99]
	v_add_u32_e32 v94, s26, v164
	v_cvt_pk_fp8_f32 v47, v90, v91 op_sel:[0,0,1]
	ds_write_b64 v94, v[92:93]
	v_pk_mul_f32 v[84:85], v[84:85], v[100:101] op_sel_hi:[1,0]
	v_pk_mul_f32 v[86:87], v[86:87], v[100:101] op_sel_hi:[1,0]
	global_store_dword v[96:97], v47, off offset:512
	v_cvt_pk_bf16_f32 v92, v88, v89
	v_cvt_pk_bf16_f32 v93, v90, v91
	v_pk_fma_f32 v[84:85], v[132:133], v[84:85], v[14:15]
	v_lshlrev_b32_e32 v47, 16, v92
	v_sub_f32_e32 v47, v88, v47
	v_and_b32_e32 v88, 0xffff0000, v92
	v_sub_f32_e32 v88, v89, v88
	v_cvt_pk_bf16_f32 v88, v47, v88
	v_lshlrev_b32_e32 v47, 16, v93
	v_and_b32_e32 v89, 0xffff0000, v93
	v_sub_f32_e32 v47, v90, v47
	v_sub_f32_e32 v89, v91, v89
	v_cvt_pk_bf16_f32 v89, v47, v89
	v_mov_b32_e32 v47, v101
	v_cvt_pk_fp8_f32 v47, v84, v85
	v_pk_fma_f32 v[86:87], v[130:131], v[86:87], v[16:17]
	v_add_u32_e32 v90, s15, v165
	ds_write_b64 v90, v[92:93]
	v_cvt_pk_fp8_f32 v47, v86, v87 op_sel:[0,0,1]
	v_add_u32_e32 v90, s26, v165
	ds_write_b64 v90, v[88:89]
	v_pk_mul_f32 v[80:81], v[80:81], v[100:101] op_sel_hi:[1,0]
	global_store_dword v[96:97], v47, off offset:768
	v_cvt_pk_bf16_f32 v88, v84, v85
	v_cvt_pk_bf16_f32 v89, v86, v87
	v_pk_fma_f32 v[80:81], v[136:137], v[80:81], v[18:19]
	v_lshlrev_b32_e32 v47, 16, v88
	v_sub_f32_e32 v47, v84, v47
	v_and_b32_e32 v84, 0xffff0000, v88
	v_sub_f32_e32 v84, v85, v84
	v_cvt_pk_bf16_f32 v84, v47, v84
	v_lshlrev_b32_e32 v47, 16, v89
	v_and_b32_e32 v85, 0xffff0000, v89
	v_sub_f32_e32 v47, v86, v47
	v_sub_f32_e32 v85, v87, v85
	v_cvt_pk_bf16_f32 v85, v47, v85
	v_mov_b32_e32 v47, v101
	v_cvt_pk_fp8_f32 v47, v80, v81
	v_pk_mul_f32 v[82:83], v[82:83], v[100:101] op_sel_hi:[1,0]
	v_add_u32_e32 v86, s15, v166
	v_pk_fma_f32 v[82:83], v[134:135], v[82:83], v[20:21]
	ds_write_b64 v86, v[88:89]
	v_cvt_pk_fp8_f32 v47, v82, v83 op_sel:[0,0,1]
	v_add_u32_e32 v86, s26, v166
	ds_write_b64 v86, v[84:85]
	v_pk_mul_f32 v[76:77], v[76:77], v[100:101] op_sel_hi:[1,0]
	global_store_dword v[96:97], v47, off offset:1024
	v_cvt_pk_bf16_f32 v84, v80, v81
	v_cvt_pk_bf16_f32 v85, v82, v83
	v_pk_fma_f32 v[76:77], v[140:141], v[76:77], v[22:23]
	v_lshlrev_b32_e32 v47, 16, v84
	v_sub_f32_e32 v47, v80, v47
	v_and_b32_e32 v80, 0xffff0000, v84
	v_sub_f32_e32 v80, v81, v80
	v_cvt_pk_bf16_f32 v80, v47, v80
	v_lshlrev_b32_e32 v47, 16, v85
	v_and_b32_e32 v81, 0xffff0000, v85
	v_sub_f32_e32 v47, v82, v47
	v_sub_f32_e32 v81, v83, v81
	v_cvt_pk_bf16_f32 v81, v47, v81
	v_mov_b32_e32 v47, v101
	v_cvt_pk_fp8_f32 v47, v76, v77
	v_pk_mul_f32 v[78:79], v[78:79], v[100:101] op_sel_hi:[1,0]
	v_add_u32_e32 v82, s15, v167
	v_pk_fma_f32 v[78:79], v[138:139], v[78:79], v[24:25]
	ds_write_b64 v82, v[84:85]
	v_cvt_pk_fp8_f32 v47, v78, v79 op_sel:[0,0,1]
	v_add_u32_e32 v82, s26, v167
	ds_write_b64 v82, v[80:81]
	v_pk_mul_f32 v[72:73], v[72:73], v[100:101] op_sel_hi:[1,0]
	global_store_dword v[96:97], v47, off offset:1280
	v_cvt_pk_bf16_f32 v80, v76, v77
	v_cvt_pk_bf16_f32 v81, v78, v79
	v_pk_fma_f32 v[72:73], v[144:145], v[72:73], v[26:27]
	v_lshlrev_b32_e32 v47, 16, v80
	v_sub_f32_e32 v47, v76, v47
	v_and_b32_e32 v76, 0xffff0000, v80
	v_sub_f32_e32 v76, v77, v76
	v_cvt_pk_bf16_f32 v76, v47, v76
	v_lshlrev_b32_e32 v47, 16, v81
	v_and_b32_e32 v77, 0xffff0000, v81
	v_sub_f32_e32 v47, v78, v47
	v_sub_f32_e32 v77, v79, v77
	v_cvt_pk_bf16_f32 v77, v47, v77
	v_mov_b32_e32 v47, v101
	v_cvt_pk_fp8_f32 v47, v72, v73
	v_pk_mul_f32 v[74:75], v[74:75], v[100:101] op_sel_hi:[1,0]
	v_add_u32_e32 v78, s15, v168
	v_pk_fma_f32 v[74:75], v[142:143], v[74:75], v[28:29]
	ds_write_b64 v78, v[80:81]
	v_cvt_pk_fp8_f32 v47, v74, v75 op_sel:[0,0,1]
	v_add_u32_e32 v78, s26, v168
	ds_write_b64 v78, v[76:77]
	v_pk_mul_f32 v[68:69], v[68:69], v[100:101] op_sel_hi:[1,0]
	global_store_dword v[96:97], v47, off offset:1536
	v_cvt_pk_bf16_f32 v76, v72, v73
	v_cvt_pk_bf16_f32 v77, v74, v75
	v_pk_fma_f32 v[68:69], v[148:149], v[68:69], v[30:31]
	v_lshlrev_b32_e32 v47, 16, v76
	v_sub_f32_e32 v47, v72, v47
	v_and_b32_e32 v72, 0xffff0000, v76
	v_sub_f32_e32 v72, v73, v72
	v_cvt_pk_bf16_f32 v72, v47, v72
	v_lshlrev_b32_e32 v47, 16, v77
	v_sub_f32_e32 v47, v74, v47
	v_and_b32_e32 v73, 0xffff0000, v77
	v_sub_f32_e32 v73, v75, v73
	v_cvt_pk_bf16_f32 v73, v47, v73
	v_add_u32_e32 v47, s15, v169
	ds_write_b64 v47, v[76:77]
	s_waitcnt lgkmcnt(1)
	s_nop 1
	v_add_f32_dpp v47, v194, v194 quad_perm:[1,0,3,2] row_mask:0xf bank_mask:0xf
	v_mov_b32_e32 v75, v101
	v_cvt_pk_fp8_f32 v75, v68, v69
	v_pk_mul_f32 v[70:71], v[70:71], v[100:101] op_sel_hi:[1,0]
	v_add_u32_e32 v76, s26, v169
	s_waitcnt lgkmcnt(0)
	s_nop 1
	v_add_f32_dpp v47, v47, v47 quad_perm:[2,3,0,1] row_mask:0xf bank_mask:0xf
	v_pk_fma_f32 v[70:71], v[146:147], v[70:71], v[32:33]
	ds_write_b64 v76, v[72:73]
	v_cvt_pk_fp8_f32 v75, v70, v71 op_sel:[0,0,1]
	v_mov_b32_e32 v46, 0
	s_waitcnt lgkmcnt(1)
	s_nop 1
	v_add_f32_dpp v47, v47, v47 row_half_mirror row_mask:0xf bank_mask:0xf
	global_store_dword v[96:97], v75, off offset:1792
	v_cvt_pk_bf16_f32 v72, v68, v69
	v_cvt_pk_bf16_f32 v73, v70, v71
	s_waitcnt lgkmcnt(0)
	s_nop 1
	v_add_f32_dpp v47, v47, v47 row_mirror row_mask:0xf bank_mask:0xf
	ds_bpermute_b32 v74, v155, v47
	v_lshlrev_b32_e32 v75, 16, v72
	v_sub_f32_e32 v68, v68, v75
	v_and_b32_e32 v75, 0xffff0000, v72
	v_sub_f32_e32 v69, v69, v75
	s_waitcnt lgkmcnt(0)
	v_add_f32_e32 v47, v47, v74
	ds_bpermute_b32 v74, v156, v47
	v_cvt_pk_bf16_f32 v68, v68, v69
	v_lshlrev_b32_e32 v69, 16, v73
	v_sub_f32_e32 v69, v70, v69
	v_and_b32_e32 v70, 0xffff0000, v73
	s_waitcnt lgkmcnt(0)
	v_add_f32_e32 v47, v47, v74
	v_fmamk_f32 v47, v47, 0x3a000000, v182
	v_mul_f32_e32 v74, 0x4f800000, v47
	v_cmp_gt_f32_e32 vcc, s31, v47
	v_sub_f32_e32 v70, v71, v70
	v_cvt_pk_bf16_f32 v69, v69, v70
	v_add_u32_e32 v70, s15, v170
	v_cndmask_b32_e32 v47, v47, v74, vcc
	v_sqrt_f32_e32 v74, v47
	ds_write_b64 v70, v[72:73]
	v_add_u32_e32 v70, s26, v170
	ds_write_b64 v70, v[68:69]
	v_add_u32_e32 v71, -1, v74
	v_fma_f32 v75, -v71, v74, v47
	v_cmp_ge_f32_e64 s[10:11], 0, v75
	v_add_u32_e32 v75, 1, v74
	s_nop 0
	v_cndmask_b32_e64 v71, v74, v71, s[10:11]
	v_fma_f32 v74, -v75, v74, v47
	v_cmp_lt_f32_e64 s[10:11], 0, v74
	s_nop 1
	v_cndmask_b32_e64 v71, v71, v75, s[10:11]
	v_mul_f32_e32 v74, 0x37800000, v71
	v_cndmask_b32_e32 v71, v71, v74, vcc
	v_cmp_class_f32_e32 vcc, v47, v183
	s_nop 1
	v_cndmask_b32_e32 v47, v71, v47, vcc
	v_div_scale_f32 v71, s[10:11], v47, v47, 1.0
	v_rcp_f32_e32 v74, v71
	s_add_i32 s10, s35, s27
	s_ashr_i32 s11, s10, 31
	s_lshl_b64 s[10:11], s[10:11], 11
	v_fma_f32 v68, -v71, v74, 1.0
	v_fmac_f32_e32 v74, v68, v74
	v_div_scale_f32 v68, vcc, 1.0, v47, 1.0
	v_mul_f32_e32 v69, v68, v74
	v_fma_f32 v70, -v71, v69, v68
	v_fmac_f32_e32 v69, v70, v74
	v_fma_f32 v68, -v71, v69, v68
	v_div_fmas_f32 v68, v68, v74, v69
	v_div_fixup_f32 v68, v68, v47, 1.0
	v_pk_mul_f32 v[64:65], v[64:65], v[68:69] op_sel_hi:[1,0]
	v_mov_b32_e32 v47, v101
	v_pk_fma_f32 v[70:71], v[120:121], v[64:65], v[2:3]
	v_pk_mul_f32 v[64:65], v[66:67], v[68:69] op_sel_hi:[1,0]
	v_cvt_pk_fp8_f32 v47, v70, v71
	v_pk_fma_f32 v[66:67], v[118:119], v[64:65], v[4:5]
	v_lshl_add_u64 v[64:65], v[116:117], 0, s[10:11]
	s_mov_b64 s[10:11], -1
	v_cvt_pk_fp8_f32 v47, v66, v67 op_sel:[0,0,1]
	global_store_dword v[64:65], v47, off
	v_cvt_pk_bf16_f32 v72, v70, v71
	v_cvt_pk_bf16_f32 v73, v66, v67
	s_nop 0
	v_lshlrev_b32_e32 v47, 16, v72
	v_sub_f32_e32 v47, v70, v47
	v_and_b32_e32 v69, 0xffff0000, v72
	v_sub_f32_e32 v69, v71, v69
	v_cvt_pk_bf16_f32 v70, v47, v69
	v_lshlrev_b32_e32 v47, 16, v73
	v_sub_f32_e32 v47, v66, v47
	v_and_b32_e32 v66, 0xffff0000, v73
	v_pk_mul_f32 v[60:61], v[60:61], v[68:69] op_sel_hi:[1,0]
	v_sub_f32_e32 v66, v67, v66
	v_cvt_pk_bf16_f32 v71, v47, v66
	v_pk_fma_f32 v[60:61], v[124:125], v[60:61], v[6:7]
	v_mov_b32_e32 v47, v101
	v_cvt_pk_fp8_f32 v47, v60, v61
	v_pk_mul_f32 v[62:63], v[62:63], v[68:69] op_sel_hi:[1,0]
	v_add_u32_e32 v66, s28, v163
	v_pk_fma_f32 v[62:63], v[122:123], v[62:63], v[8:9]
	ds_write_b64 v66, v[72:73]
	v_cvt_pk_fp8_f32 v47, v62, v63 op_sel:[0,0,1]
	v_add_u32_e32 v66, s29, v163
	ds_write_b64 v66, v[70:71]
	v_pk_mul_f32 v[56:57], v[56:57], v[68:69] op_sel_hi:[1,0]
	global_store_dword v[64:65], v47, off offset:256
	v_cvt_pk_bf16_f32 v66, v60, v61
	v_cvt_pk_bf16_f32 v67, v62, v63
	v_pk_fma_f32 v[56:57], v[128:129], v[56:57], v[10:11]
	v_lshlrev_b32_e32 v47, 16, v66
	v_sub_f32_e32 v47, v60, v47
	v_and_b32_e32 v60, 0xffff0000, v66
	v_sub_f32_e32 v60, v61, v60
	v_cvt_pk_bf16_f32 v60, v47, v60
	v_lshlrev_b32_e32 v47, 16, v67
	v_and_b32_e32 v61, 0xffff0000, v67
	v_sub_f32_e32 v47, v62, v47
	v_sub_f32_e32 v61, v63, v61
	v_cvt_pk_bf16_f32 v61, v47, v61
	v_mov_b32_e32 v47, v101
	v_cvt_pk_fp8_f32 v47, v56, v57
	v_pk_mul_f32 v[58:59], v[58:59], v[68:69] op_sel_hi:[1,0]
	v_add_u32_e32 v62, s28, v164
	v_pk_fma_f32 v[58:59], v[126:127], v[58:59], v[12:13]
	ds_write_b64 v62, v[66:67]
	v_cvt_pk_fp8_f32 v47, v58, v59 op_sel:[0,0,1]
	v_add_u32_e32 v62, s29, v164
	ds_write_b64 v62, v[60:61]
	v_pk_mul_f32 v[52:53], v[52:53], v[68:69] op_sel_hi:[1,0]
	global_store_dword v[64:65], v47, off offset:512
	v_cvt_pk_bf16_f32 v60, v56, v57
	v_cvt_pk_bf16_f32 v61, v58, v59
	v_pk_fma_f32 v[52:53], v[132:133], v[52:53], v[14:15]
	v_lshlrev_b32_e32 v47, 16, v60
	v_sub_f32_e32 v47, v56, v47
	v_and_b32_e32 v56, 0xffff0000, v60
	v_sub_f32_e32 v56, v57, v56
	v_cvt_pk_bf16_f32 v56, v47, v56
	v_lshlrev_b32_e32 v47, 16, v61
	v_and_b32_e32 v57, 0xffff0000, v61
	v_sub_f32_e32 v47, v58, v47
	v_sub_f32_e32 v57, v59, v57
	v_cvt_pk_bf16_f32 v57, v47, v57
	v_mov_b32_e32 v47, v101
	v_cvt_pk_fp8_f32 v47, v52, v53
	v_pk_mul_f32 v[54:55], v[54:55], v[68:69] op_sel_hi:[1,0]
	v_add_u32_e32 v58, s28, v165
	v_pk_fma_f32 v[54:55], v[130:131], v[54:55], v[16:17]
	ds_write_b64 v58, v[60:61]
	v_cvt_pk_fp8_f32 v47, v54, v55 op_sel:[0,0,1]
	v_add_u32_e32 v58, s29, v165
	ds_write_b64 v58, v[56:57]
	v_pk_mul_f32 v[48:49], v[48:49], v[68:69] op_sel_hi:[1,0]
	global_store_dword v[64:65], v47, off offset:768
	v_cvt_pk_bf16_f32 v56, v52, v53
	v_cvt_pk_bf16_f32 v57, v54, v55
	v_pk_fma_f32 v[48:49], v[136:137], v[48:49], v[18:19]
	v_lshlrev_b32_e32 v47, 16, v56
	v_sub_f32_e32 v47, v52, v47
	v_and_b32_e32 v52, 0xffff0000, v56
	v_sub_f32_e32 v52, v53, v52
	v_cvt_pk_bf16_f32 v52, v47, v52
	v_lshlrev_b32_e32 v47, 16, v57
	v_and_b32_e32 v53, 0xffff0000, v57
	v_sub_f32_e32 v47, v54, v47
	v_sub_f32_e32 v53, v55, v53
	v_cvt_pk_bf16_f32 v53, v47, v53
	v_mov_b32_e32 v47, v101
	v_cvt_pk_fp8_f32 v47, v48, v49
	v_pk_mul_f32 v[50:51], v[50:51], v[68:69] op_sel_hi:[1,0]
	v_add_u32_e32 v54, s28, v166
	v_pk_fma_f32 v[50:51], v[134:135], v[50:51], v[20:21]
	ds_write_b64 v54, v[56:57]
	v_cvt_pk_fp8_f32 v47, v50, v51 op_sel:[0,0,1]
	v_add_u32_e32 v54, s29, v166
	ds_write_b64 v54, v[52:53]
	v_pk_mul_f32 v[42:43], v[42:43], v[68:69] op_sel_hi:[1,0]
	global_store_dword v[64:65], v47, off offset:1024
	v_cvt_pk_bf16_f32 v52, v48, v49
	v_cvt_pk_bf16_f32 v53, v50, v51
	v_pk_fma_f32 v[42:43], v[140:141], v[42:43], v[22:23]
	v_lshlrev_b32_e32 v47, 16, v52
	v_sub_f32_e32 v47, v48, v47
	v_and_b32_e32 v48, 0xffff0000, v52
	v_sub_f32_e32 v48, v49, v48
	v_cvt_pk_bf16_f32 v48, v47, v48
	v_lshlrev_b32_e32 v47, 16, v53
	v_and_b32_e32 v49, 0xffff0000, v53
	v_sub_f32_e32 v47, v50, v47
	v_sub_f32_e32 v49, v51, v49
	v_cvt_pk_bf16_f32 v49, v47, v49
	v_mov_b32_e32 v47, v101
	v_cvt_pk_fp8_f32 v47, v42, v43
	v_pk_mul_f32 v[44:45], v[44:45], v[68:69] op_sel_hi:[1,0]
	v_add_u32_e32 v50, s28, v167
	v_pk_fma_f32 v[44:45], v[138:139], v[44:45], v[24:25]
	ds_write_b64 v50, v[52:53]
	v_cvt_pk_fp8_f32 v47, v44, v45 op_sel:[0,0,1]
	v_add_u32_e32 v50, s29, v167
	ds_write_b64 v50, v[48:49]
	v_pk_mul_f32 v[38:39], v[38:39], v[68:69] op_sel_hi:[1,0]
	global_store_dword v[64:65], v47, off offset:1280
	v_cvt_pk_bf16_f32 v48, v42, v43
	v_cvt_pk_bf16_f32 v49, v44, v45
	v_pk_fma_f32 v[38:39], v[144:145], v[38:39], v[26:27]
	v_lshlrev_b32_e32 v47, 16, v48
	v_sub_f32_e32 v42, v42, v47
	v_and_b32_e32 v47, 0xffff0000, v48
	v_sub_f32_e32 v43, v43, v47
	v_cvt_pk_bf16_f32 v42, v42, v43
	v_lshlrev_b32_e32 v43, 16, v49
	v_sub_f32_e32 v43, v44, v43
	v_and_b32_e32 v44, 0xffff0000, v49
	v_sub_f32_e32 v44, v45, v44
	v_cvt_pk_bf16_f32 v43, v43, v44
	v_mov_b32_e32 v44, v101
	v_cvt_pk_fp8_f32 v44, v38, v39
	v_pk_mul_f32 v[40:41], v[40:41], v[68:69] op_sel_hi:[1,0]
	v_add_u32_e32 v45, s28, v168
	v_pk_fma_f32 v[40:41], v[142:143], v[40:41], v[28:29]
	ds_write_b64 v45, v[48:49]
	v_cvt_pk_fp8_f32 v44, v40, v41 op_sel:[0,0,1]
	v_add_u32_e32 v45, s29, v168
	ds_write_b64 v45, v[42:43]
	v_pk_mul_f32 v[34:35], v[34:35], v[68:69] op_sel_hi:[1,0]
	global_store_dword v[64:65], v44, off offset:1536
	v_cvt_pk_bf16_f32 v42, v38, v39
	v_cvt_pk_bf16_f32 v43, v40, v41
	v_pk_fma_f32 v[34:35], v[148:149], v[34:35], v[30:31]
	v_lshlrev_b32_e32 v44, 16, v42
	v_sub_f32_e32 v38, v38, v44
	v_and_b32_e32 v44, 0xffff0000, v42
	v_sub_f32_e32 v39, v39, v44
	v_cvt_pk_bf16_f32 v38, v38, v39
	v_lshlrev_b32_e32 v39, 16, v43
	v_sub_f32_e32 v39, v40, v39
	v_and_b32_e32 v40, 0xffff0000, v43
	v_sub_f32_e32 v40, v41, v40
	v_cvt_pk_bf16_f32 v39, v39, v40
	v_mov_b32_e32 v40, v101
	v_cvt_pk_fp8_f32 v40, v34, v35
	v_pk_mul_f32 v[36:37], v[36:37], v[68:69] op_sel_hi:[1,0]
	v_add_u32_e32 v41, s28, v169
	v_pk_fma_f32 v[36:37], v[146:147], v[36:37], v[32:33]
	ds_write_b64 v41, v[42:43]
	v_cvt_pk_fp8_f32 v40, v36, v37 op_sel:[0,0,1]
	v_add_u32_e32 v41, s29, v169
	ds_write_b64 v41, v[38:39]
	v_mov_b32_e32 v47, v46
	global_store_dword v[64:65], v40, off offset:1792
	v_cvt_pk_bf16_f32 v38, v34, v35
	v_cvt_pk_bf16_f32 v39, v36, v37
	v_mov_b32_e32 v48, v46
	v_lshlrev_b32_e32 v40, 16, v38
	v_sub_f32_e32 v34, v34, v40
	v_and_b32_e32 v40, 0xffff0000, v38
	v_sub_f32_e32 v35, v35, v40
	v_cvt_pk_bf16_f32 v34, v34, v35
	v_lshlrev_b32_e32 v35, 16, v39
	v_sub_f32_e32 v35, v36, v35
	v_and_b32_e32 v36, 0xffff0000, v39
	v_sub_f32_e32 v36, v37, v36
	v_cvt_pk_bf16_f32 v35, v35, v36
	v_add_u32_e32 v36, s28, v170
	ds_write_b64 v36, v[38:39]
	v_add_u32_e32 v36, s29, v170
	ds_write_b64 v36, v[34:35]
	s_waitcnt lgkmcnt(0)
	s_barrier
	v_mov_b32_e32 v49, v46
	v_mov_b32_e32 v34, v46
	v_mov_b32_e32 v35, v46
	v_mov_b32_e32 v36, v46
	v_mov_b32_e32 v37, v46

.LBB0_1734:
	s_waitcnt vmcnt(39)
	v_lshlrev_b32_e32 v216, 16, v198
	v_and_b32_e32 v217, 0xffff0000, v198
	v_lshlrev_b32_e32 v198, 16, v199
	v_and_b32_e32 v199, 0xffff0000, v199
	v_pk_add_f32 v[198:199], v[198:199], 0 op_sel_hi:[1,0]
	s_waitcnt vmcnt(38)
	v_lshlrev_b32_e32 v218, 16, v196
	v_and_b32_e32 v219, 0xffff0000, v196
	v_lshlrev_b32_e32 v196, 16, v197
	v_and_b32_e32 v197, 0xffff0000, v197
	s_waitcnt vmcnt(31)
	v_lshlrev_b32_e32 v232, 16, v182
	v_and_b32_e32 v233, 0xffff0000, v182
	v_lshlrev_b32_e32 v182, 16, v183
	v_and_b32_e32 v183, 0xffff0000, v183
	v_pk_add_f32 v[196:197], v[196:197], 0 op_sel_hi:[1,0]
	v_lshlrev_b32_e32 v220, 16, v194
	v_and_b32_e32 v221, 0xffff0000, v194
	v_lshlrev_b32_e32 v194, 16, v195
	v_and_b32_e32 v195, 0xffff0000, v195
	v_pk_add_f32 v[182:183], v[198:199], v[182:183]
	s_waitcnt vmcnt(30)
	v_lshlrev_b32_e32 v198, 16, v180
	v_and_b32_e32 v199, 0xffff0000, v180
	v_lshlrev_b32_e32 v180, 16, v181
	v_and_b32_e32 v181, 0xffff0000, v181
	v_pk_add_f32 v[220:221], v[220:221], 0 op_sel_hi:[1,0]
	v_pk_add_f32 v[194:195], v[194:195], 0 op_sel_hi:[1,0]
	v_lshlrev_b32_e32 v222, 16, v192
	v_and_b32_e32 v223, 0xffff0000, v192
	v_lshlrev_b32_e32 v192, 16, v193
	v_and_b32_e32 v193, 0xffff0000, v193
	v_pk_add_f32 v[180:181], v[196:197], v[180:181]
	s_waitcnt vmcnt(29)
	v_lshlrev_b32_e32 v196, 16, v178
	v_and_b32_e32 v197, 0xffff0000, v178
	v_lshlrev_b32_e32 v178, 16, v179
	v_and_b32_e32 v179, 0xffff0000, v179
	v_pk_add_f32 v[192:193], v[192:193], 0 op_sel_hi:[1,0]
	v_lshlrev_b32_e32 v224, 16, v190
	v_and_b32_e32 v225, 0xffff0000, v190
	v_lshlrev_b32_e32 v190, 16, v191
	v_and_b32_e32 v191, 0xffff0000, v191
	v_pk_add_f32 v[178:179], v[194:195], v[178:179]
	v_pk_add_f32 v[194:195], v[220:221], v[196:197]
	s_waitcnt vmcnt(28)
	v_lshlrev_b32_e32 v196, 16, v176
	v_and_b32_e32 v197, 0xffff0000, v176
	v_lshlrev_b32_e32 v176, 16, v177
	v_and_b32_e32 v177, 0xffff0000, v177
	v_pk_add_f32 v[190:191], v[190:191], 0 op_sel_hi:[1,0]
	v_lshlrev_b32_e32 v226, 16, v188
	v_and_b32_e32 v227, 0xffff0000, v188
	v_lshlrev_b32_e32 v188, 16, v189
	v_and_b32_e32 v189, 0xffff0000, v189
	v_pk_add_f32 v[176:177], v[192:193], v[176:177]
	s_waitcnt vmcnt(27)
	v_lshlrev_b32_e32 v192, 16, v174
	v_and_b32_e32 v193, 0xffff0000, v174
	v_lshlrev_b32_e32 v174, 16, v175
	v_and_b32_e32 v175, 0xffff0000, v175
	v_pk_add_f32 v[226:227], v[226:227], 0 op_sel_hi:[1,0]
	v_pk_add_f32 v[188:189], v[188:189], 0 op_sel_hi:[1,0]
	v_lshlrev_b32_e32 v228, 16, v186
	v_and_b32_e32 v229, 0xffff0000, v186
	v_lshlrev_b32_e32 v186, 16, v187
	v_and_b32_e32 v187, 0xffff0000, v187
	v_pk_add_f32 v[174:175], v[190:191], v[174:175]
	s_waitcnt vmcnt(26)
	v_lshlrev_b32_e32 v190, 16, v172
	v_and_b32_e32 v191, 0xffff0000, v172
	v_lshlrev_b32_e32 v172, 16, v173
	v_and_b32_e32 v173, 0xffff0000, v173
	v_pk_add_f32 v[186:187], v[186:187], 0 op_sel_hi:[1,0]
	v_lshlrev_b32_e32 v230, 16, v184
	v_and_b32_e32 v231, 0xffff0000, v184
	v_lshlrev_b32_e32 v184, 16, v185
	v_and_b32_e32 v185, 0xffff0000, v185
	v_pk_add_f32 v[172:173], v[188:189], v[172:173]
	v_pk_add_f32 v[188:189], v[226:227], v[190:191]
	s_waitcnt vmcnt(25)
	v_lshlrev_b32_e32 v190, 16, v170
	v_and_b32_e32 v191, 0xffff0000, v170
	v_lshlrev_b32_e32 v170, 16, v171
	v_and_b32_e32 v171, 0xffff0000, v171
	v_pk_add_f32 v[216:217], v[216:217], 0 op_sel_hi:[1,0]
	v_pk_add_f32 v[184:185], v[184:185], 0 op_sel_hi:[1,0]
	v_pk_add_f32 v[170:171], v[186:187], v[170:171]
	s_waitcnt vmcnt(24)
	v_lshlrev_b32_e32 v186, 16, v168
	v_and_b32_e32 v187, 0xffff0000, v168
	v_lshlrev_b32_e32 v168, 16, v169
	v_and_b32_e32 v169, 0xffff0000, v169
	v_pk_add_f32 v[218:219], v[218:219], 0 op_sel_hi:[1,0]
	v_pk_add_f32 v[216:217], v[216:217], v[232:233]
	v_pk_add_f32 v[168:169], v[184:185], v[168:169]
	s_waitcnt vmcnt(23)
	v_lshlrev_b32_e32 v184, 16, v166
	v_and_b32_e32 v185, 0xffff0000, v166
	v_lshlrev_b32_e32 v166, 16, v167
	v_and_b32_e32 v167, 0xffff0000, v167
	v_pk_add_f32 v[198:199], v[218:219], v[198:199]
	v_pk_add_f32 v[166:167], v[182:183], v[166:167]
	v_pk_add_f32 v[182:183], v[216:217], v[184:185]
	s_waitcnt vmcnt(22)
	v_lshlrev_b32_e32 v184, 16, v164
	v_and_b32_e32 v185, 0xffff0000, v164
	v_lshlrev_b32_e32 v164, 16, v165
	v_and_b32_e32 v165, 0xffff0000, v165
	v_pk_add_f32 v[222:223], v[222:223], 0 op_sel_hi:[1,0]
	v_pk_add_f32 v[164:165], v[180:181], v[164:165]
	v_pk_add_f32 v[180:181], v[198:199], v[184:185]
	s_waitcnt vmcnt(21)
	v_lshlrev_b32_e32 v184, 16, v162
	v_and_b32_e32 v185, 0xffff0000, v162
	v_lshlrev_b32_e32 v162, 16, v163
	v_and_b32_e32 v163, 0xffff0000, v163
	v_pk_add_f32 v[224:225], v[224:225], 0 op_sel_hi:[1,0]
	v_pk_add_f32 v[196:197], v[222:223], v[196:197]
	v_pk_add_f32 v[162:163], v[178:179], v[162:163]
	s_waitcnt vmcnt(20)
	v_lshlrev_b32_e32 v178, 16, v160
	v_and_b32_e32 v179, 0xffff0000, v160
	v_lshlrev_b32_e32 v160, 16, v161
	v_and_b32_e32 v161, 0xffff0000, v161
	v_pk_add_f32 v[192:193], v[224:225], v[192:193]
	v_pk_add_f32 v[160:161], v[176:177], v[160:161]
	v_pk_add_f32 v[176:177], v[196:197], v[178:179]
	s_waitcnt vmcnt(19)
	v_lshlrev_b32_e32 v178, 16, v158
	v_and_b32_e32 v179, 0xffff0000, v158
	v_lshlrev_b32_e32 v158, 16, v159
	v_and_b32_e32 v159, 0xffff0000, v159
	v_pk_add_f32 v[228:229], v[228:229], 0 op_sel_hi:[1,0]
	v_pk_add_f32 v[158:159], v[174:175], v[158:159]
	v_pk_add_f32 v[174:175], v[192:193], v[178:179]
	s_waitcnt vmcnt(18)
	v_lshlrev_b32_e32 v178, 16, v156
	v_and_b32_e32 v179, 0xffff0000, v156
	v_lshlrev_b32_e32 v156, 16, v157
	v_and_b32_e32 v157, 0xffff0000, v157
	v_pk_add_f32 v[230:231], v[230:231], 0 op_sel_hi:[1,0]
	v_pk_add_f32 v[190:191], v[228:229], v[190:191]
	v_pk_add_f32 v[156:157], v[172:173], v[156:157]
	s_waitcnt vmcnt(17)
	v_lshlrev_b32_e32 v172, 16, v154
	v_and_b32_e32 v173, 0xffff0000, v154
	v_lshlrev_b32_e32 v154, 16, v155
	v_and_b32_e32 v155, 0xffff0000, v155
	v_pk_add_f32 v[186:187], v[230:231], v[186:187]
	v_pk_add_f32 v[154:155], v[170:171], v[154:155]
	v_pk_add_f32 v[170:171], v[190:191], v[172:173]
	s_waitcnt vmcnt(16)
	v_lshlrev_b32_e32 v172, 16, v152
	v_and_b32_e32 v173, 0xffff0000, v152
	v_lshlrev_b32_e32 v152, 16, v153
	v_and_b32_e32 v153, 0xffff0000, v153
	v_pk_add_f32 v[152:153], v[168:169], v[152:153]
	v_pk_add_f32 v[168:169], v[186:187], v[172:173]
	s_waitcnt vmcnt(15)
	v_lshlrev_b32_e32 v172, 16, v150
	v_and_b32_e32 v173, 0xffff0000, v150
	v_lshlrev_b32_e32 v150, 16, v151
	v_and_b32_e32 v151, 0xffff0000, v151
	v_pk_add_f32 v[150:151], v[166:167], v[150:151]
	s_waitcnt vmcnt(14)
	v_lshlrev_b32_e32 v166, 16, v148
	v_and_b32_e32 v167, 0xffff0000, v148
	v_lshlrev_b32_e32 v148, 16, v149
	v_and_b32_e32 v149, 0xffff0000, v149
	v_pk_add_f32 v[184:185], v[194:195], v[184:185]
	v_pk_add_f32 v[148:149], v[164:165], v[148:149]
	s_waitcnt vmcnt(13)
	v_lshlrev_b32_e32 v164, 16, v146
	v_and_b32_e32 v165, 0xffff0000, v146
	v_lshlrev_b32_e32 v146, 16, v147
	v_and_b32_e32 v147, 0xffff0000, v147
	v_pk_add_f32 v[146:147], v[162:163], v[146:147]
	v_pk_add_f32 v[162:163], v[184:185], v[164:165]
	s_waitcnt vmcnt(12)
	v_lshlrev_b32_e32 v164, 16, v144
	v_and_b32_e32 v165, 0xffff0000, v144
	v_lshlrev_b32_e32 v144, 16, v145
	v_and_b32_e32 v145, 0xffff0000, v145
	v_pk_add_f32 v[144:145], v[160:161], v[144:145]
	s_waitcnt vmcnt(11)
	v_lshlrev_b32_e32 v160, 16, v142
	v_and_b32_e32 v161, 0xffff0000, v142
	v_lshlrev_b32_e32 v142, 16, v143
	v_and_b32_e32 v143, 0xffff0000, v143
	v_pk_add_f32 v[178:179], v[188:189], v[178:179]
	v_pk_add_f32 v[142:143], v[158:159], v[142:143]
	s_waitcnt vmcnt(10)
	v_lshlrev_b32_e32 v158, 16, v140
	v_and_b32_e32 v159, 0xffff0000, v140
	v_lshlrev_b32_e32 v140, 16, v141
	v_and_b32_e32 v141, 0xffff0000, v141
	v_pk_add_f32 v[140:141], v[156:157], v[140:141]
	v_pk_add_f32 v[156:157], v[178:179], v[158:159]
	s_waitcnt vmcnt(9)
	v_lshlrev_b32_e32 v158, 16, v138
	v_and_b32_e32 v159, 0xffff0000, v138
	v_lshlrev_b32_e32 v138, 16, v139
	v_and_b32_e32 v139, 0xffff0000, v139
	v_pk_add_f32 v[172:173], v[182:183], v[172:173]
	v_pk_add_f32 v[166:167], v[180:181], v[166:167]
	v_pk_add_f32 v[138:139], v[154:155], v[138:139]
	s_waitcnt vmcnt(8)
	v_lshlrev_b32_e32 v154, 16, v136
	v_and_b32_e32 v155, 0xffff0000, v136
	v_lshlrev_b32_e32 v136, 16, v137
	v_and_b32_e32 v137, 0xffff0000, v137
	v_pk_add_f32 v[136:137], v[152:153], v[136:137]
	s_waitcnt vmcnt(7)
	v_pk_fma_f32 v[96:97], v[172:173], v[128:129], v[96:97]
	s_waitcnt vmcnt(6)
	v_pk_fma_f32 v[92:93], v[166:167], v[124:125], v[92:93]
	v_pk_add_f32 v[158:159], v[170:171], v[158:159]
	v_pk_add_f32 v[154:155], v[168:169], v[154:155]
	v_pk_fma_f32 v[98:99], v[150:151], v[130:131], v[98:99]
	v_pk_fma_f32 v[94:95], v[148:149], v[126:127], v[94:95]
	s_waitcnt vmcnt(0)
	v_pk_fma_f32 v[102:103], v[136:137], v[102:103], v[70:71]
	v_mov_b32_e32 v70, v97
	v_mov_b32_e32 v71, v93
	v_pk_fma_f32 v[72:73], v[158:159], v[104:105], v[72:73]
	v_pk_fma_f32 v[100:101], v[154:155], v[100:101], v[68:69]
	v_mov_b32_e32 v68, v96
	v_mov_b32_e32 v69, v92
	v_pk_mul_f32 v[70:71], v[70:71], v[70:71]
	v_mov_b32_e32 v104, v99
	v_mov_b32_e32 v105, v95
	v_pk_fma_f32 v[68:69], v[68:69], v[68:69], v[70:71]
	v_mov_b32_e32 v70, v98
	v_mov_b32_e32 v71, v94
	v_pk_mul_f32 v[104:105], v[104:105], v[104:105]
	v_pk_fma_f32 v[88:89], v[162:163], v[120:121], v[88:89]
	v_pk_fma_f32 v[90:91], v[146:147], v[122:123], v[90:91]
	v_pk_fma_f32 v[70:71], v[70:71], v[70:71], v[104:105]
	v_pk_mul_f32 v[104:105], v[88:89], v[88:89]
	v_pk_add_f32 v[68:69], v[68:69], v[70:71]
	v_pk_mul_f32 v[70:71], v[90:91], v[90:91]
	v_pk_add_f32 v[160:161], v[174:175], v[160:161]
	v_pk_fma_f32 v[74:75], v[138:139], v[106:107], v[74:75]
	v_pk_mov_b32 v[106:107], v[104:105], v[70:71] op_sel:[1,0]
	v_mov_b32_e32 v105, v71
	v_pk_fma_f32 v[80:81], v[160:161], v[112:113], v[80:81]
	v_pk_add_f32 v[70:71], v[106:107], v[104:105]
	v_pk_add_f32 v[164:165], v[176:177], v[164:165]
	v_mul_f32_e32 v104, v80, v80
	v_mul_f32_e32 v105, v81, v81
	v_pk_add_f32 v[68:69], v[68:69], v[68:69] op_sel:[0,1] op_sel_hi:[1,0]
	v_pk_add_f32 v[70:71], v[70:71], v[70:71] op_sel:[0,1] op_sel_hi:[1,0]
	v_pk_fma_f32 v[86:87], v[144:145], v[118:119], v[86:87]
	v_pk_fma_f32 v[84:85], v[164:165], v[116:117], v[84:85]
	v_mov_b32_e32 v69, v104
	v_mov_b32_e32 v71, v105
	v_pk_fma_f32 v[82:83], v[142:143], v[114:115], v[82:83]
	v_pk_add_f32 v[68:69], v[68:69], v[70:71]
	v_mul_f32_e32 v70, v85, v85
	v_mul_f32_e32 v104, v87, v87
	v_mul_f32_e32 v106, v82, v82
	v_mul_f32_e32 v107, v83, v83
	v_pk_fma_f32 v[70:71], v[84:85], v[84:85], v[70:71] op_sel_hi:[1,1,0]
	v_pk_fma_f32 v[104:105], v[86:87], v[86:87], v[104:105] op_sel_hi:[1,1,0]
	v_mov_b32_e32 v71, v106
	v_mov_b32_e32 v105, v107
	v_pk_fma_f32 v[76:77], v[156:157], v[108:109], v[76:77]
	v_pk_fma_f32 v[78:79], v[140:141], v[110:111], v[78:79]
	v_pk_add_f32 v[70:71], v[70:71], v[104:105]
	v_pk_mul_f32 v[104:105], v[76:77], v[76:77]
	v_pk_add_f32 v[68:69], v[68:69], v[70:71]
	v_pk_mul_f32 v[70:71], v[78:79], v[78:79]
	v_pk_add_f32 v[68:69], v[68:69], v[68:69] op_sel:[0,1] op_sel_hi:[1,0]
	v_pk_mov_b32 v[106:107], v[104:105], v[70:71] op_sel:[1,0]
	v_mov_b32_e32 v105, v71
	v_pk_add_f32 v[70:71], v[106:107], v[104:105]
	v_mul_f32_e32 v104, v100, v100
	v_mul_f32_e32 v105, v101, v101
	v_pk_add_f32 v[70:71], v[70:71], v[70:71] op_sel:[0,1] op_sel_hi:[1,0]
	v_mov_b32_e32 v69, v104
	v_mov_b32_e32 v71, v105
	v_pk_add_f32 v[68:69], v[68:69], v[70:71]
	v_mul_f32_e32 v70, v73, v73
	v_mul_f32_e32 v104, v75, v75
	v_mul_f32_e32 v106, v102, v102
	v_mul_f32_e32 v107, v103, v103
	v_pk_fma_f32 v[70:71], v[72:73], v[72:73], v[70:71] op_sel_hi:[1,1,0]
	v_pk_fma_f32 v[104:105], v[74:75], v[74:75], v[104:105] op_sel_hi:[1,1,0]
	v_mov_b32_e32 v71, v106
	v_mov_b32_e32 v105, v107
	v_pk_add_f32 v[70:71], v[70:71], v[104:105]
	v_lshl_add_u64 v[106:107], s[4:5], 0, v[132:133]
	v_pk_add_f32 v[68:69], v[68:69], v[70:71]
	s_add_u32 s4, s4, s6
	v_add_f32_e32 v68, v68, v69
	s_addc_u32 s5, s5, s7
	s_add_u32 s8, s8, s6
	s_addc_u32 s9, s9, s7
	s_add_u32 s10, s10, s12
	s_waitcnt lgkmcnt(0)
	s_nop 1
	v_add_f32_dpp v68, v68, v68 quad_perm:[1,0,3,2] row_mask:0xf bank_mask:0xf
	s_addc_u32 s11, s11, s13
	s_waitcnt lgkmcnt(0)
	s_nop 1
	v_add_f32_dpp v68, v68, v68 quad_perm:[2,3,0,1] row_mask:0xf bank_mask:0xf
	s_waitcnt lgkmcnt(0)
	s_nop 1
	v_add_f32_dpp v68, v68, v68 row_half_mirror row_mask:0xf bank_mask:0xf
	ds_bpermute_b32 v69, v203, v68
	s_waitcnt lgkmcnt(0)
	v_add_f32_e32 v68, v68, v69
	ds_bpermute_b32 v69, v204, v68
	s_waitcnt lgkmcnt(0)
	v_add_f32_e32 v68, v68, v69
	ds_bpermute_b32 v69, v205, v68
	s_waitcnt lgkmcnt(0)
	v_add_f32_e32 v68, v68, v69
	v_fmamk_f32 v68, v68, 0x3a000000, v214
	v_mul_f32_e32 v69, 0x4f800000, v68
	v_cmp_gt_f32_e32 vcc, s16, v68
	s_nop 1
	v_cndmask_b32_e32 v68, v68, v69, vcc
	v_sqrt_f32_e32 v69, v68
	s_nop 0
	v_add_u32_e32 v70, -1, v69
	v_fma_f32 v71, -v70, v69, v68
	v_cmp_ge_f32_e64 s[0:1], 0, v71
	v_add_u32_e32 v71, 1, v69
	s_nop 0
	v_cndmask_b32_e64 v70, v69, v70, s[0:1]
	v_fma_f32 v69, -v71, v69, v68
	v_cmp_lt_f32_e64 s[0:1], 0, v69
	s_nop 1
	v_cndmask_b32_e64 v69, v70, v71, s[0:1]
	v_mul_f32_e32 v70, 0x37800000, v69
	v_cndmask_b32_e32 v69, v69, v70, vcc
	v_cmp_class_f32_e32 vcc, v68, v215
	s_nop 1
	v_cndmask_b32_e32 v68, v69, v68, vcc
	v_div_scale_f32 v69, s[0:1], v68, v68, 1.0
	v_rcp_f32_e32 v70, v69
	s_nop 0
	v_fma_f32 v71, -v69, v70, 1.0
	v_fmac_f32_e32 v70, v71, v70
	v_div_scale_f32 v71, vcc, 1.0, v68, 1.0
	v_mul_f32_e32 v104, v71, v70
	v_fma_f32 v105, -v69, v104, v71
	v_fmac_f32_e32 v104, v105, v70
	v_fma_f32 v69, -v69, v104, v71
	v_div_fmas_f32 v69, v69, v70, v104
	v_div_fixup_f32 v104, v69, v68, 1.0
	v_pk_mul_f32 v[68:69], v[96:97], v[104:105] op_sel_hi:[1,0]
	v_pk_mul_f32 v[70:71], v[98:99], v[104:105] op_sel_hi:[1,0]
	v_pk_mul_f32 v[68:69], v[28:29], v[68:69]
	v_pk_mul_f32 v[70:71], v[30:31], v[70:71]
	global_store_dwordx4 v[106:107], v[68:71], off nt
	v_mov_b64_e32 v[98:99], v[50:51]
	v_mov_b64_e32 v[96:97], v[48:49]
	v_pk_mul_f32 v[68:69], v[92:93], v[104:105] op_sel_hi:[1,0]
	v_pk_mul_f32 v[70:71], v[94:95], v[104:105] op_sel_hi:[1,0]
	v_pk_mul_f32 v[68:69], v[0:1], v[68:69]
	v_pk_mul_f32 v[70:71], v[2:3], v[70:71]
	global_store_dwordx4 v[106:107], v[68:71], off offset:1024 nt
	v_mov_b64_e32 v[94:95], v[46:47]
	v_mov_b64_e32 v[92:93], v[44:45]
	v_pk_mul_f32 v[68:69], v[88:89], v[104:105] op_sel_hi:[1,0]
	v_pk_mul_f32 v[70:71], v[90:91], v[104:105] op_sel_hi:[1,0]
	v_pk_mul_f32 v[68:69], v[4:5], v[68:69]
	v_pk_mul_f32 v[70:71], v[6:7], v[70:71]
	global_store_dwordx4 v[106:107], v[68:71], off offset:2048 nt
	v_mov_b64_e32 v[90:91], v[42:43]
	v_mov_b64_e32 v[88:89], v[40:41]
	v_pk_mul_f32 v[68:69], v[84:85], v[104:105] op_sel_hi:[1,0]
	v_pk_mul_f32 v[70:71], v[86:87], v[104:105] op_sel_hi:[1,0]
	v_pk_mul_f32 v[68:69], v[8:9], v[68:69]
	v_pk_mul_f32 v[70:71], v[10:11], v[70:71]
	global_store_dwordx4 v[106:107], v[68:71], off offset:3072 nt
	v_mov_b64_e32 v[86:87], v[38:39]
	v_mov_b64_e32 v[84:85], v[36:37]
	v_pk_mul_f32 v[68:69], v[80:81], v[104:105] op_sel_hi:[1,0]
	v_pk_mul_f32 v[70:71], v[82:83], v[104:105] op_sel_hi:[1,0]
	v_add_co_u32_e32 v80, vcc, s17, v106
	v_pk_mul_f32 v[70:71], v[26:27], v[70:71]
	v_pk_mul_f32 v[68:69], v[24:25], v[68:69]
	v_addc_co_u32_e32 v81, vcc, 0, v107, vcc
	global_store_dwordx4 v[80:81], v[68:71], off nt
	s_andn2_b64 vcc, exec, s[14:15]
	s_nop 0
	v_pk_mul_f32 v[68:69], v[76:77], v[104:105] op_sel_hi:[1,0]
	v_pk_mul_f32 v[70:71], v[78:79], v[104:105] op_sel_hi:[1,0]
	v_pk_mul_f32 v[68:69], v[20:21], v[68:69]
	v_pk_mul_f32 v[70:71], v[22:23], v[70:71]
	global_store_dwordx4 v[80:81], v[68:71], off offset:1024 nt
	v_mov_b64_e32 v[78:79], v[62:63]
	v_mov_b64_e32 v[76:77], v[60:61]
	v_pk_mul_f32 v[68:69], v[72:73], v[104:105] op_sel_hi:[1,0]
	v_pk_mul_f32 v[70:71], v[74:75], v[104:105] op_sel_hi:[1,0]
	v_pk_mul_f32 v[68:69], v[16:17], v[68:69]
	v_pk_mul_f32 v[70:71], v[18:19], v[70:71]
	global_store_dwordx4 v[80:81], v[68:71], off offset:2048 nt
	v_mov_b64_e32 v[74:75], v[58:59]
	v_mov_b64_e32 v[72:73], v[56:57]
	v_pk_mul_f32 v[68:69], v[100:101], v[104:105] op_sel_hi:[1,0]
	v_pk_mul_f32 v[70:71], v[102:103], v[104:105] op_sel_hi:[1,0]
	v_pk_mul_f32 v[68:69], v[12:13], v[68:69]
	v_pk_mul_f32 v[70:71], v[14:15], v[70:71]
	global_store_dwordx4 v[80:81], v[68:71], off offset:3072 nt
	v_mov_b64_e32 v[82:83], v[66:67]
	v_mov_b64_e32 v[80:81], v[64:65]
	v_mov_b64_e32 v[70:71], v[54:55]
	v_mov_b64_e32 v[68:69], v[52:53]
	s_cbranch_vccz .LBB0_1737
.LBB0_1735:
	s_waitcnt vmcnt(0)
	v_readfirstlane_b32 s0, v32
	v_readfirstlane_b32 s14, v33
	s_ashr_i32 s1, s0, 31
	v_readfirstlane_b32 s18, v34
	s_lshl_b64 s[0:1], s[0:1], 12
	s_ashr_i32 s15, s14, 31
	v_readfirstlane_b32 s20, v35
	v_lshl_add_u64 v[100:101], v[134:135], 0, s[0:1]
	s_lshl_b64 s[0:1], s[14:15], 12
	s_ashr_i32 s19, s18, 31
	global_load_dwordx2 v[198:199], v[100:101], off nt
	global_load_dwordx2 v[196:197], v[100:101], off offset:512 nt
	global_load_dwordx2 v[194:195], v[100:101], off offset:1024 nt
	global_load_dwordx2 v[192:193], v[100:101], off offset:1536 nt
	global_load_dwordx2 v[190:191], v[100:101], off offset:2048 nt
	global_load_dwordx2 v[188:189], v[100:101], off offset:2560 nt
	global_load_dwordx2 v[186:187], v[100:101], off offset:3072 nt
	global_load_dwordx2 v[184:185], v[100:101], off offset:3584 nt
	v_lshl_add_u64 v[100:101], v[134:135], 0, s[0:1]
	s_lshl_b64 s[0:1], s[18:19], 12
	s_ashr_i32 s21, s20, 31
	global_load_dwordx2 v[182:183], v[100:101], off nt
	global_load_dwordx2 v[180:181], v[100:101], off offset:512 nt
	global_load_dwordx2 v[178:179], v[100:101], off offset:1024 nt
	global_load_dwordx2 v[176:177], v[100:101], off offset:1536 nt
	global_load_dwordx2 v[174:175], v[100:101], off offset:2048 nt
	global_load_dwordx2 v[172:173], v[100:101], off offset:2560 nt
	global_load_dwordx2 v[170:171], v[100:101], off offset:3072 nt
	global_load_dwordx2 v[168:169], v[100:101], off offset:3584 nt
	v_lshl_add_u64 v[100:101], v[134:135], 0, s[0:1]
	s_lshl_b64 s[0:1], s[20:21], 12
	global_load_dwordx2 v[166:167], v[100:101], off nt
	global_load_dwordx2 v[164:165], v[100:101], off offset:512 nt
	global_load_dwordx2 v[162:163], v[100:101], off offset:1024 nt
	global_load_dwordx2 v[160:161], v[100:101], off offset:1536 nt
	global_load_dwordx2 v[158:159], v[100:101], off offset:2048 nt
	global_load_dwordx2 v[156:157], v[100:101], off offset:2560 nt
	global_load_dwordx2 v[154:155], v[100:101], off offset:3072 nt
	global_load_dwordx2 v[152:153], v[100:101], off offset:3584 nt
	v_lshl_add_u64 v[100:101], v[134:135], 0, s[0:1]
	s_ashr_i32 s0, s44, 31
	s_lshr_b32 s0, s0, 21
	s_add_i32 s0, s44, s0
	s_ashr_i32 s0, s0, 11
	s_mul_hi_i32 s1, s0, 0xc000
	s_mul_i32 s0, s0, 0xc000
	s_add_u32 s0, s2, s0
	s_addc_u32 s1, s3, s1
	s_add_u32 s0, s0, 0xd0a000
	s_addc_u32 s1, s1, 0
	global_load_dwordx2 v[150:151], v[100:101], off nt
	global_load_dwordx2 v[148:149], v[100:101], off offset:512 nt
	global_load_dwordx2 v[146:147], v[100:101], off offset:1024 nt
	global_load_dwordx2 v[144:145], v[100:101], off offset:1536 nt
	global_load_dwordx2 v[142:143], v[100:101], off offset:2048 nt
	global_load_dwordx2 v[140:141], v[100:101], off offset:2560 nt
	global_load_dwordx2 v[138:139], v[100:101], off offset:3072 nt
	global_load_dwordx2 v[136:137], v[100:101], off offset:3584 nt
	global_load_dwordx4 v[128:131], v206, s[0:1]
	global_load_dwordx4 v[124:127], v207, s[0:1]
	global_load_dwordx4 v[120:123], v208, s[0:1]
	global_load_dwordx4 v[116:119], v209, s[0:1]
	global_load_dwordx4 v[112:115], v210, s[0:1]
	global_load_dwordx4 v[108:111], v211, s[0:1]
	global_load_dwordx4 v[104:107], v212, s[0:1]
	global_load_dwordx4 v[100:103], v213, s[0:1]
	s_add_i32 s44, s44, s40
	s_cmpk_gt_i32 s44, 0x3fff
	s_cselect_b64 s[14:15], -1, 0
	s_and_b64 vcc, exec, s[14:15]
	s_cbranch_vccnz .LBB0_1734
	v_lshl_add_u64 v[32:33], s[8:9], 0, v[132:133]
	v_add_co_u32_e32 v34, vcc, 0x50000000, v32
	s_nop 1
	v_addc_co_u32_e32 v35, vcc, 0, v33, vcc
	v_add_co_u32_e32 v32, vcc, 0x50001000, v32
	global_load_dwordx4 v[48:51], v[34:35], off nt
	global_load_dwordx4 v[44:47], v[34:35], off offset:1024 nt
	global_load_dwordx4 v[40:43], v[34:35], off offset:2048 nt
	global_load_dwordx4 v[36:39], v[34:35], off offset:3072 nt
	v_addc_co_u32_e32 v33, vcc, 0, v33, vcc
	global_load_dwordx4 v[64:67], v[32:33], off nt
	global_load_dwordx4 v[60:63], v[32:33], off offset:1024 nt
	global_load_dwordx4 v[56:59], v[32:33], off offset:2048 nt
	global_load_dwordx4 v[52:55], v[32:33], off offset:3072 nt
	s_nop 0
	global_load_dwordx4 v[32:35], v133, s[10:11]
	s_branch .LBB0_1734
